# c41 + LN epilogues of phases 6,8,13: gamma/beta loads of store groups 2-4 hoisted in front of the first write-through store group (no vmcnt(0) behind write-through stores)
# baseline (speedup 1.0000x reference)
.LBB0_1015:
	s_or_b64 exec, exec, s[6:7]
	s_waitcnt lgkmcnt(0)
	s_barrier
	v_lshl_add_u64 v[140:141], s[16:17], 0, v[132:133]
	v_lshl_add_u64 v[144:145], s[18:19], 0, v[132:133]
	global_load_dwordx4 v[128:131], v[140:141], off
	global_load_dwordx4 v[132:135], v[144:145], off
	v_or_b32_e32 v153, s0, v138
	v_lshl_add_u32 v152, v153, 3, 0
	ds_read_b64 v[156:157], v152 offset:8192
	v_add_u32_e32 v148, s3, v153
	v_ashrrev_i32_e32 v149, 31, v148
	v_lshlrev_b64 v[142:143], 10, v[148:149]
	v_mov_b32_e32 v154, 0x7fc00000
	s_waitcnt lgkmcnt(0)
	v_sub_f32_e32 v117, v117, v156
	v_sub_f32_e32 v116, v116, v156
	v_sub_f32_e32 v119, v119, v156
	v_sub_f32_e32 v118, v118, v156
	v_pk_mul_f32 v[118:119], v[156:157], v[118:119] op_sel:[1,0]
	v_pk_mul_f32 v[116:117], v[156:157], v[116:117] op_sel:[1,0]
	s_cmp_lg_u64 s[14:15], 0
	v_lshl_add_u64 v[138:139], v[142:143], 0, v[136:137]
	v_cmp_eq_u32_e64 s[4:5], 0, v150
	s_cselect_b64 s[8:9], -1, 0
	v_lshl_add_u64 v[146:147], v[138:139], 2, s[12:13]
	s_cmp_eq_u64 s[14:15], 0
	global_load_dwordx4 v[188:191], v[140:141], off offset:64
	global_load_dwordx4 v[192:195], v[144:145], off offset:64
	global_load_dwordx4 v[196:199], v[140:141], off offset:512
	global_load_dwordx4 v[200:203], v[144:145], off offset:512
	global_load_dwordx4 v[204:207], v[140:141], off offset:576
	global_load_dwordx4 v[208:211], v[144:145], off offset:576
	s_waitcnt vmcnt(0)
	v_pk_fma_f32 v[116:117], v[128:129], v[116:117], v[132:133]
	v_pk_fma_f32 v[118:119], v[130:131], v[118:119], v[134:135]
	v_cndmask_b32_e64 v117, v154, v117, s[4:5]
	v_cndmask_b32_e64 v119, v154, v119, s[4:5]
	v_cndmask_b32_e64 v118, v154, v118, s[4:5]
	v_cndmask_b32_e64 v116, v154, v116, s[4:5]
	global_store_dwordx4 v[146:147], v[116:119], off sc1
	s_cbranch_scc1 .LBB0_1017
	s_nop 0
	v_cvt_pk_bf16_f32 v116, v116, v117
	v_cvt_pk_bf16_f32 v117, v118, v119
	v_lshl_add_u64 v[118:119], v[138:139], 1, s[34:35]
	global_store_dwordx2 v[118:119], v[116:117], off sc1

.LBB0_1031:
	ds_read_b64 v[134:135], v152 offset:8192
	v_mov_b32_e32 v132, 0x7fc00000
	v_lshl_add_u64 v[130:131], v[136:137], 0, 16
	s_and_b64 vcc, exec, s[6:7]
	s_waitcnt lgkmcnt(0)
	v_sub_f32_e32 v81, v81, v134
	v_sub_f32_e32 v80, v80, v134
	v_sub_f32_e32 v83, v83, v134
	v_sub_f32_e32 v82, v82, v134
	v_pk_mul_f32 v[82:83], v[134:135], v[82:83] op_sel:[1,0]
	v_pk_mul_f32 v[80:81], v[134:135], v[80:81] op_sel:[1,0]
	v_pk_fma_f32 v[82:83], v[190:191], v[82:83], v[194:195]
	v_pk_fma_f32 v[80:81], v[188:189], v[80:81], v[192:193]
	v_cndmask_b32_e64 v83, v132, v83, s[4:5]
	v_cndmask_b32_e64 v82, v132, v82, s[4:5]
	v_cndmask_b32_e64 v81, v132, v81, s[4:5]
	v_cndmask_b32_e64 v80, v132, v80, s[4:5]
	global_store_dwordx4 v[146:147], v[80:83], off offset:64 sc1
	s_cbranch_vccnz .LBB0_1033
	v_lshl_add_u64 v[134:135], v[142:143], 0, v[130:131]
	v_cvt_pk_bf16_f32 v80, v80, v81
	v_cvt_pk_bf16_f32 v81, v82, v83
	v_lshl_add_u64 v[82:83], v[134:135], 1, s[34:35]
	global_store_dwordx2 v[82:83], v[80:81], off sc1
.LBB0_1033:
	ds_read_b64 v[80:81], v152 offset:8320
	s_and_b64 vcc, exec, s[6:7]
	s_waitcnt lgkmcnt(0)
	v_sub_f32_e32 v83, v85, v80
	v_sub_f32_e32 v82, v84, v80
	v_sub_f32_e32 v85, v87, v80
	v_sub_f32_e32 v84, v86, v80
	v_pk_mul_f32 v[84:85], v[80:81], v[84:85] op_sel:[1,0]
	v_pk_mul_f32 v[80:81], v[80:81], v[82:83] op_sel:[1,0]
	v_pk_fma_f32 v[82:83], v[190:191], v[84:85], v[194:195]
	v_pk_fma_f32 v[80:81], v[188:189], v[80:81], v[192:193]
	v_cndmask_b32_e64 v83, v132, v83, s[4:5]
	v_cndmask_b32_e64 v82, v132, v82, s[4:5]
	v_cndmask_b32_e64 v81, v132, v81, s[4:5]
	v_cndmask_b32_e64 v80, v132, v80, s[4:5]
	global_store_dwordx4 v[126:127], v[80:83], off offset:64 sc1
	s_cbranch_vccnz .LBB0_1035
	v_lshl_add_u64 v[84:85], v[138:139], 0, v[130:131]
	v_cvt_pk_bf16_f32 v80, v80, v81
	v_cvt_pk_bf16_f32 v81, v82, v83
	v_lshl_add_u64 v[82:83], v[84:85], 1, s[34:35]
	global_store_dwordx2 v[82:83], v[80:81], off sc1
.LBB0_1035:
	ds_read_b64 v[80:81], v152 offset:8448
	s_and_b64 vcc, exec, s[6:7]
	s_waitcnt lgkmcnt(0)
	v_sub_f32_e32 v83, v97, v80
	v_sub_f32_e32 v82, v96, v80
	v_sub_f32_e32 v85, v99, v80
	v_sub_f32_e32 v84, v98, v80
	v_pk_mul_f32 v[84:85], v[80:81], v[84:85] op_sel:[1,0]
	v_pk_mul_f32 v[80:81], v[80:81], v[82:83] op_sel:[1,0]
	v_pk_fma_f32 v[82:83], v[190:191], v[84:85], v[194:195]
	v_pk_fma_f32 v[80:81], v[188:189], v[80:81], v[192:193]
	v_mov_b32_e32 v84, 0x7fc00000
	v_cndmask_b32_e64 v83, v84, v83, s[4:5]
	v_cndmask_b32_e64 v82, v84, v82, s[4:5]
	v_cndmask_b32_e64 v81, v84, v81, s[4:5]
	v_cndmask_b32_e64 v80, v84, v80, s[4:5]
	global_store_dwordx4 v[120:121], v[80:83], off offset:64 sc1
	s_cbranch_vccnz .LBB0_1037
	v_lshl_add_u64 v[86:87], v[124:125], 0, v[130:131]
	v_cvt_pk_bf16_f32 v80, v80, v81
	v_cvt_pk_bf16_f32 v81, v82, v83
	v_lshl_add_u64 v[82:83], v[86:87], 1, s[34:35]
	global_store_dwordx2 v[82:83], v[80:81], off sc1
.LBB0_1037:
	ds_read_b64 v[80:81], v152 offset:8576
	s_and_b64 vcc, exec, s[6:7]
	s_waitcnt lgkmcnt(0)
	v_sub_f32_e32 v83, v101, v80
	v_sub_f32_e32 v82, v100, v80
	v_sub_f32_e32 v87, v103, v80
	v_sub_f32_e32 v86, v102, v80
	v_pk_mul_f32 v[86:87], v[80:81], v[86:87] op_sel:[1,0]
	v_pk_mul_f32 v[80:81], v[80:81], v[82:83] op_sel:[1,0]
	v_pk_fma_f32 v[82:83], v[190:191], v[86:87], v[194:195]
	v_pk_fma_f32 v[80:81], v[188:189], v[80:81], v[192:193]
	v_cndmask_b32_e64 v83, v84, v83, s[4:5]
	v_cndmask_b32_e64 v82, v84, v82, s[4:5]
	v_cndmask_b32_e64 v81, v84, v81, s[4:5]
	v_cndmask_b32_e64 v80, v84, v80, s[4:5]
	global_store_dwordx4 v[118:119], v[80:83], off offset:64 sc1
	s_cbranch_vccnz .LBB0_1039
	v_lshl_add_u64 v[84:85], v[116:117], 0, v[130:131]
	v_cvt_pk_bf16_f32 v80, v80, v81
	v_cvt_pk_bf16_f32 v81, v82, v83
	v_lshl_add_u64 v[82:83], v[84:85], 1, s[34:35]
	global_store_dwordx2 v[82:83], v[80:81], off sc1
.LBB0_1039:
	ds_read_b64 v[80:81], v152 offset:9216
	s_and_b64 vcc, exec, s[6:7]
	s_waitcnt lgkmcnt(0)
	v_sub_f32_e32 v83, v105, v80
	v_sub_f32_e32 v82, v104, v80
	v_sub_f32_e32 v85, v107, v80
	v_sub_f32_e32 v84, v106, v80
	v_pk_mul_f32 v[84:85], v[80:81], v[84:85] op_sel:[1,0]
	v_pk_mul_f32 v[80:81], v[80:81], v[82:83] op_sel:[1,0]
	v_pk_fma_f32 v[82:83], v[190:191], v[84:85], v[194:195]
	v_pk_fma_f32 v[80:81], v[188:189], v[80:81], v[192:193]
	v_mov_b32_e32 v84, 0x7fc00000
	v_cndmask_b32_e64 v83, v84, v83, s[4:5]
	v_cndmask_b32_e64 v82, v84, v82, s[4:5]
	v_cndmask_b32_e64 v81, v84, v81, s[4:5]
	v_cndmask_b32_e64 v80, v84, v80, s[4:5]
	global_store_dwordx4 v[114:115], v[80:83], off offset:64 sc1
	s_cbranch_vccnz .LBB0_1041
	v_lshl_add_u64 v[86:87], v[112:113], 0, v[130:131]
	v_cvt_pk_bf16_f32 v80, v80, v81
	v_cvt_pk_bf16_f32 v81, v82, v83
	v_lshl_add_u64 v[82:83], v[86:87], 1, s[34:35]
	global_store_dwordx2 v[82:83], v[80:81], off sc1
.LBB0_1041:
	ds_read_b64 v[80:81], v152 offset:9344
	s_and_b64 vcc, exec, s[6:7]
	s_waitcnt lgkmcnt(0)
	v_sub_f32_e32 v83, v89, v80
	v_sub_f32_e32 v82, v88, v80
	v_sub_f32_e32 v87, v91, v80
	v_sub_f32_e32 v86, v90, v80
	v_pk_mul_f32 v[86:87], v[80:81], v[86:87] op_sel:[1,0]
	v_pk_mul_f32 v[80:81], v[80:81], v[82:83] op_sel:[1,0]
	v_pk_fma_f32 v[82:83], v[190:191], v[86:87], v[194:195]
	v_pk_fma_f32 v[80:81], v[188:189], v[80:81], v[192:193]
	v_cndmask_b32_e64 v83, v84, v83, s[4:5]
	v_cndmask_b32_e64 v82, v84, v82, s[4:5]
	v_cndmask_b32_e64 v81, v84, v81, s[4:5]
	v_cndmask_b32_e64 v80, v84, v80, s[4:5]
	global_store_dwordx4 v[110:111], v[80:83], off offset:64 sc1
	s_cbranch_vccnz .LBB0_1043
	v_lshl_add_u64 v[84:85], v[108:109], 0, v[130:131]
	v_cvt_pk_bf16_f32 v80, v80, v81
	v_cvt_pk_bf16_f32 v81, v82, v83
	v_lshl_add_u64 v[82:83], v[84:85], 1, s[34:35]
	global_store_dwordx2 v[82:83], v[80:81], off sc1
.LBB0_1043:
	ds_read_b64 v[80:81], v152 offset:9472
	s_and_b64 vcc, exec, s[6:7]
	s_waitcnt lgkmcnt(0)
	v_sub_f32_e32 v73, v73, v80
	v_sub_f32_e32 v72, v72, v80
	v_sub_f32_e32 v75, v75, v80
	v_sub_f32_e32 v74, v74, v80
	v_pk_mul_f32 v[74:75], v[80:81], v[74:75] op_sel:[1,0]
	v_pk_mul_f32 v[72:73], v[80:81], v[72:73] op_sel:[1,0]
	v_pk_fma_f32 v[74:75], v[190:191], v[74:75], v[194:195]
	v_pk_fma_f32 v[72:73], v[188:189], v[72:73], v[192:193]
	v_mov_b32_e32 v80, 0x7fc00000
	v_cndmask_b32_e64 v75, v80, v75, s[4:5]
	v_cndmask_b32_e64 v74, v80, v74, s[4:5]
	v_cndmask_b32_e64 v73, v80, v73, s[4:5]
	v_cndmask_b32_e64 v72, v80, v72, s[4:5]
	global_store_dwordx4 v[122:123], v[72:75], off offset:64 sc1
	s_cbranch_vccnz .LBB0_1045
	v_lshl_add_u64 v[82:83], v[92:93], 0, v[130:131]
	v_cvt_pk_bf16_f32 v72, v72, v73
	v_cvt_pk_bf16_f32 v73, v74, v75
	v_lshl_add_u64 v[74:75], v[82:83], 1, s[34:35]
	global_store_dwordx2 v[74:75], v[72:73], off sc1
.LBB0_1045:
	ds_read_b64 v[72:73], v152 offset:9600
	s_and_b64 vcc, exec, s[6:7]
	s_waitcnt lgkmcnt(0)
	v_sub_f32_e32 v49, v49, v72
	v_sub_f32_e32 v48, v48, v72
	v_sub_f32_e32 v51, v51, v72
	v_sub_f32_e32 v50, v50, v72
	v_pk_mul_f32 v[50:51], v[72:73], v[50:51] op_sel:[1,0]
	v_pk_mul_f32 v[48:49], v[72:73], v[48:49] op_sel:[1,0]
	v_pk_fma_f32 v[50:51], v[190:191], v[50:51], v[194:195]
	v_pk_fma_f32 v[48:49], v[188:189], v[48:49], v[192:193]
	v_cndmask_b32_e64 v51, v80, v51, s[4:5]
	v_cndmask_b32_e64 v50, v80, v50, s[4:5]
	v_cndmask_b32_e64 v49, v80, v49, s[4:5]
	v_cndmask_b32_e64 v48, v80, v48, s[4:5]
	global_store_dwordx4 v[128:129], v[48:51], off offset:64 sc1
	s_cbranch_vccnz .LBB0_1047
	v_lshl_add_u64 v[52:53], v[94:95], 0, v[130:131]
	v_cvt_pk_bf16_f32 v48, v48, v49
	v_cvt_pk_bf16_f32 v49, v50, v51
	v_lshl_add_u64 v[50:51], v[52:53], 1, s[34:35]
	global_store_dwordx2 v[50:51], v[48:49], off sc1
.LBB0_1047:
	ds_read_b64 v[76:77], v152 offset:8192
	s_mov_b64 s[0:1], 0x80
	v_mov_b32_e32 v74, 0x7fc00000
	v_lshl_add_u64 v[72:73], v[136:137], 0, s[0:1]
	s_and_b64 vcc, exec, s[6:7]
	s_waitcnt lgkmcnt(0)
	v_sub_f32_e32 v29, v29, v76
	v_sub_f32_e32 v28, v28, v76
	v_sub_f32_e32 v31, v31, v76
	v_sub_f32_e32 v30, v30, v76
	v_pk_mul_f32 v[30:31], v[76:77], v[30:31] op_sel:[1,0]
	v_pk_mul_f32 v[28:29], v[76:77], v[28:29] op_sel:[1,0]
	v_pk_fma_f32 v[30:31], v[198:199], v[30:31], v[202:203]
	v_pk_fma_f32 v[28:29], v[196:197], v[28:29], v[200:201]
	v_cndmask_b32_e64 v31, v74, v31, s[4:5]
	v_cndmask_b32_e64 v30, v74, v30, s[4:5]
	v_cndmask_b32_e64 v29, v74, v29, s[4:5]
	v_cndmask_b32_e64 v28, v74, v28, s[4:5]
	global_store_dwordx4 v[146:147], v[28:31], off offset:512 sc1
	s_cbranch_vccnz .LBB0_1049
	v_lshl_add_u64 v[76:77], v[142:143], 0, v[72:73]
	v_cvt_pk_bf16_f32 v28, v28, v29
	v_cvt_pk_bf16_f32 v29, v30, v31
	v_lshl_add_u64 v[30:31], v[76:77], 1, s[34:35]
	global_store_dwordx2 v[30:31], v[28:29], off sc1
.LBB0_1049:
	ds_read_b64 v[28:29], v152 offset:8320
	s_and_b64 vcc, exec, s[6:7]
	s_waitcnt lgkmcnt(0)
	v_sub_f32_e32 v31, v41, v28
	v_sub_f32_e32 v30, v40, v28
	v_sub_f32_e32 v41, v43, v28
	v_sub_f32_e32 v40, v42, v28
	v_pk_mul_f32 v[40:41], v[28:29], v[40:41] op_sel:[1,0]
	v_pk_mul_f32 v[28:29], v[28:29], v[30:31] op_sel:[1,0]
	v_pk_fma_f32 v[30:31], v[198:199], v[40:41], v[202:203]
	v_pk_fma_f32 v[28:29], v[196:197], v[28:29], v[200:201]
	v_cndmask_b32_e64 v31, v74, v31, s[4:5]
	v_cndmask_b32_e64 v30, v74, v30, s[4:5]
	v_cndmask_b32_e64 v29, v74, v29, s[4:5]
	v_cndmask_b32_e64 v28, v74, v28, s[4:5]
	global_store_dwordx4 v[126:127], v[28:31], off offset:512 sc1
	s_cbranch_vccnz .LBB0_1051
	v_lshl_add_u64 v[40:41], v[138:139], 0, v[72:73]
	v_cvt_pk_bf16_f32 v28, v28, v29
	v_cvt_pk_bf16_f32 v29, v30, v31
	v_lshl_add_u64 v[30:31], v[40:41], 1, s[34:35]
	global_store_dwordx2 v[30:31], v[28:29], off sc1
.LBB0_1051:
	ds_read_b64 v[28:29], v152 offset:8448
	s_and_b64 vcc, exec, s[6:7]
	s_waitcnt lgkmcnt(0)
	v_sub_f32_e32 v31, v45, v28
	v_sub_f32_e32 v30, v44, v28
	v_sub_f32_e32 v41, v47, v28
	v_sub_f32_e32 v40, v46, v28
	v_pk_mul_f32 v[40:41], v[28:29], v[40:41] op_sel:[1,0]
	v_pk_mul_f32 v[28:29], v[28:29], v[30:31] op_sel:[1,0]
	v_pk_fma_f32 v[30:31], v[198:199], v[40:41], v[202:203]
	v_pk_fma_f32 v[28:29], v[196:197], v[28:29], v[200:201]
	v_mov_b32_e32 v40, 0x7fc00000
	v_cndmask_b32_e64 v31, v40, v31, s[4:5]
	v_cndmask_b32_e64 v30, v40, v30, s[4:5]
	v_cndmask_b32_e64 v29, v40, v29, s[4:5]
	v_cndmask_b32_e64 v28, v40, v28, s[4:5]
	global_store_dwordx4 v[120:121], v[28:31], off offset:512 sc1
	s_cbranch_vccnz .LBB0_1053
	v_lshl_add_u64 v[42:43], v[124:125], 0, v[72:73]
	v_cvt_pk_bf16_f32 v28, v28, v29
	v_cvt_pk_bf16_f32 v29, v30, v31
	v_lshl_add_u64 v[30:31], v[42:43], 1, s[34:35]
	global_store_dwordx2 v[30:31], v[28:29], off sc1
.LBB0_1053:
	ds_read_b64 v[28:29], v152 offset:8576
	s_and_b64 vcc, exec, s[6:7]
	s_waitcnt lgkmcnt(0)
	v_sub_f32_e32 v31, v57, v28
	v_sub_f32_e32 v30, v56, v28
	v_sub_f32_e32 v43, v59, v28
	v_sub_f32_e32 v42, v58, v28
	v_pk_mul_f32 v[42:43], v[28:29], v[42:43] op_sel:[1,0]
	v_pk_mul_f32 v[28:29], v[28:29], v[30:31] op_sel:[1,0]
	v_pk_fma_f32 v[30:31], v[198:199], v[42:43], v[202:203]
	v_pk_fma_f32 v[28:29], v[196:197], v[28:29], v[200:201]
	v_cndmask_b32_e64 v31, v40, v31, s[4:5]
	v_cndmask_b32_e64 v30, v40, v30, s[4:5]
	v_cndmask_b32_e64 v29, v40, v29, s[4:5]
	v_cndmask_b32_e64 v28, v40, v28, s[4:5]
	global_store_dwordx4 v[118:119], v[28:31], off offset:512 sc1
	s_cbranch_vccnz .LBB0_1055
	v_lshl_add_u64 v[40:41], v[116:117], 0, v[72:73]
	v_cvt_pk_bf16_f32 v28, v28, v29
	v_cvt_pk_bf16_f32 v29, v30, v31
	v_lshl_add_u64 v[30:31], v[40:41], 1, s[34:35]
	global_store_dwordx2 v[30:31], v[28:29], off sc1
.LBB0_1055:
	ds_read_b64 v[28:29], v152 offset:9216
	s_and_b64 vcc, exec, s[6:7]
	s_waitcnt lgkmcnt(0)
	v_sub_f32_e32 v31, v61, v28
	v_sub_f32_e32 v30, v60, v28
	v_sub_f32_e32 v41, v63, v28
	v_sub_f32_e32 v40, v62, v28
	v_pk_mul_f32 v[40:41], v[28:29], v[40:41] op_sel:[1,0]
	v_pk_mul_f32 v[28:29], v[28:29], v[30:31] op_sel:[1,0]
	v_pk_fma_f32 v[30:31], v[198:199], v[40:41], v[202:203]
	v_pk_fma_f32 v[28:29], v[196:197], v[28:29], v[200:201]
	v_mov_b32_e32 v40, 0x7fc00000
	v_cndmask_b32_e64 v31, v40, v31, s[4:5]
	v_cndmask_b32_e64 v30, v40, v30, s[4:5]
	v_cndmask_b32_e64 v29, v40, v29, s[4:5]
	v_cndmask_b32_e64 v28, v40, v28, s[4:5]
	global_store_dwordx4 v[114:115], v[28:31], off offset:512 sc1
	s_cbranch_vccnz .LBB0_1057
	v_lshl_add_u64 v[42:43], v[112:113], 0, v[72:73]
	v_cvt_pk_bf16_f32 v28, v28, v29
	v_cvt_pk_bf16_f32 v29, v30, v31
	v_lshl_add_u64 v[30:31], v[42:43], 1, s[34:35]
	global_store_dwordx2 v[30:31], v[28:29], off sc1
.LBB0_1057:
	ds_read_b64 v[28:29], v152 offset:9344
	s_and_b64 vcc, exec, s[6:7]
	s_waitcnt lgkmcnt(0)
	v_sub_f32_e32 v31, v69, v28
	v_sub_f32_e32 v30, v68, v28
	v_sub_f32_e32 v43, v71, v28
	v_sub_f32_e32 v42, v70, v28
	v_pk_mul_f32 v[42:43], v[28:29], v[42:43] op_sel:[1,0]
	v_pk_mul_f32 v[28:29], v[28:29], v[30:31] op_sel:[1,0]
	v_pk_fma_f32 v[30:31], v[198:199], v[42:43], v[202:203]
	v_pk_fma_f32 v[28:29], v[196:197], v[28:29], v[200:201]
	v_cndmask_b32_e64 v31, v40, v31, s[4:5]
	v_cndmask_b32_e64 v30, v40, v30, s[4:5]
	v_cndmask_b32_e64 v29, v40, v29, s[4:5]
	v_cndmask_b32_e64 v28, v40, v28, s[4:5]
	global_store_dwordx4 v[110:111], v[28:31], off offset:512 sc1
	s_cbranch_vccnz .LBB0_1059
	v_lshl_add_u64 v[40:41], v[108:109], 0, v[72:73]
	v_cvt_pk_bf16_f32 v28, v28, v29
	v_cvt_pk_bf16_f32 v29, v30, v31
	v_lshl_add_u64 v[30:31], v[40:41], 1, s[34:35]
	global_store_dwordx2 v[30:31], v[28:29], off sc1
.LBB0_1059:
	ds_read_b64 v[28:29], v152 offset:9472
	s_and_b64 vcc, exec, s[6:7]
	s_waitcnt lgkmcnt(0)
	v_sub_f32_e32 v31, v65, v28
	v_sub_f32_e32 v30, v64, v28
	v_sub_f32_e32 v41, v67, v28
	v_sub_f32_e32 v40, v66, v28
	v_pk_mul_f32 v[40:41], v[28:29], v[40:41] op_sel:[1,0]
	v_pk_mul_f32 v[28:29], v[28:29], v[30:31] op_sel:[1,0]
	v_pk_fma_f32 v[30:31], v[198:199], v[40:41], v[202:203]
	v_pk_fma_f32 v[28:29], v[196:197], v[28:29], v[200:201]
	v_mov_b32_e32 v40, 0x7fc00000
	v_cndmask_b32_e64 v31, v40, v31, s[4:5]
	v_cndmask_b32_e64 v30, v40, v30, s[4:5]
	v_cndmask_b32_e64 v29, v40, v29, s[4:5]
	v_cndmask_b32_e64 v28, v40, v28, s[4:5]
	global_store_dwordx4 v[122:123], v[28:31], off offset:512 sc1
	s_cbranch_vccnz .LBB0_1061
	v_lshl_add_u64 v[42:43], v[92:93], 0, v[72:73]
	v_cvt_pk_bf16_f32 v28, v28, v29
	v_cvt_pk_bf16_f32 v29, v30, v31
	v_lshl_add_u64 v[30:31], v[42:43], 1, s[34:35]
	global_store_dwordx2 v[30:31], v[28:29], off sc1
.LBB0_1061:
	ds_read_b64 v[28:29], v152 offset:9600
	s_and_b64 vcc, exec, s[6:7]
	s_waitcnt lgkmcnt(0)
	v_sub_f32_e32 v31, v37, v28
	v_sub_f32_e32 v30, v36, v28
	v_sub_f32_e32 v37, v39, v28
	v_sub_f32_e32 v36, v38, v28
	v_pk_mul_f32 v[36:37], v[28:29], v[36:37] op_sel:[1,0]
	v_pk_mul_f32 v[28:29], v[28:29], v[30:31] op_sel:[1,0]
	v_pk_fma_f32 v[30:31], v[198:199], v[36:37], v[202:203]
	v_pk_fma_f32 v[28:29], v[196:197], v[28:29], v[200:201]
	v_cndmask_b32_e64 v31, v40, v31, s[4:5]
	v_cndmask_b32_e64 v30, v40, v30, s[4:5]
	v_cndmask_b32_e64 v29, v40, v29, s[4:5]
	v_cndmask_b32_e64 v28, v40, v28, s[4:5]
	global_store_dwordx4 v[128:129], v[28:31], off offset:512 sc1
	s_cbranch_vccnz .LBB0_1063
	v_lshl_add_u64 v[36:37], v[94:95], 0, v[72:73]
	v_cvt_pk_bf16_f32 v28, v28, v29
	v_cvt_pk_bf16_f32 v29, v30, v31
	v_lshl_add_u64 v[30:31], v[36:37], 1, s[34:35]
	global_store_dwordx2 v[30:31], v[28:29], off sc1
.LBB0_1063:
	ds_read_b64 v[44:45], v152 offset:8192
	s_mov_b64 s[0:1], 0x90
	v_mov_b32_e32 v42, 0x7fc00000
	v_lshl_add_u64 v[40:41], v[136:137], 0, s[0:1]
	s_and_b64 vcc, exec, s[6:7]
	s_waitcnt lgkmcnt(0)
	v_sub_f32_e32 v1, v1, v44
	v_sub_f32_e32 v0, v0, v44
	v_sub_f32_e32 v3, v3, v44
	v_sub_f32_e32 v2, v2, v44
	v_pk_mul_f32 v[2:3], v[44:45], v[2:3] op_sel:[1,0]
	v_pk_mul_f32 v[0:1], v[44:45], v[0:1] op_sel:[1,0]
	v_pk_fma_f32 v[2:3], v[206:207], v[2:3], v[210:211]
	v_pk_fma_f32 v[0:1], v[204:205], v[0:1], v[208:209]
	v_cndmask_b32_e64 v3, v42, v3, s[4:5]
	v_cndmask_b32_e64 v2, v42, v2, s[4:5]
	v_cndmask_b32_e64 v1, v42, v1, s[4:5]
	v_cndmask_b32_e64 v0, v42, v0, s[4:5]
	global_store_dwordx4 v[146:147], v[0:3], off offset:576 sc1
	s_cbranch_vccnz .LBB0_1065
	v_lshl_add_u64 v[44:45], v[142:143], 0, v[40:41]
	v_cvt_pk_bf16_f32 v0, v0, v1
	v_cvt_pk_bf16_f32 v1, v2, v3
	v_lshl_add_u64 v[2:3], v[44:45], 1, s[34:35]
	global_store_dwordx2 v[2:3], v[0:1], off sc1
.LBB0_1065:
	ds_read_b64 v[0:1], v152 offset:8320
	s_and_b64 vcc, exec, s[6:7]
	s_waitcnt lgkmcnt(0)
	v_sub_f32_e32 v3, v5, v0
	v_sub_f32_e32 v2, v4, v0
	v_sub_f32_e32 v5, v7, v0
	v_sub_f32_e32 v4, v6, v0
	v_pk_mul_f32 v[4:5], v[0:1], v[4:5] op_sel:[1,0]
	v_pk_mul_f32 v[0:1], v[0:1], v[2:3] op_sel:[1,0]
	v_pk_fma_f32 v[2:3], v[206:207], v[4:5], v[210:211]
	v_pk_fma_f32 v[0:1], v[204:205], v[0:1], v[208:209]
	v_cndmask_b32_e64 v3, v42, v3, s[4:5]
	v_cndmask_b32_e64 v2, v42, v2, s[4:5]
	v_cndmask_b32_e64 v1, v42, v1, s[4:5]
	v_cndmask_b32_e64 v0, v42, v0, s[4:5]
	global_store_dwordx4 v[126:127], v[0:3], off offset:576 sc1
	s_cbranch_vccnz .LBB0_1067
	v_lshl_add_u64 v[4:5], v[138:139], 0, v[40:41]
	v_cvt_pk_bf16_f32 v0, v0, v1
	v_cvt_pk_bf16_f32 v1, v2, v3
	v_lshl_add_u64 v[2:3], v[4:5], 1, s[34:35]
	global_store_dwordx2 v[2:3], v[0:1], off sc1
.LBB0_1067:
	ds_read_b64 v[0:1], v152 offset:8448
	s_and_b64 vcc, exec, s[6:7]
	s_waitcnt lgkmcnt(0)
	v_sub_f32_e32 v3, v9, v0
	v_sub_f32_e32 v2, v8, v0
	v_sub_f32_e32 v5, v11, v0
	v_sub_f32_e32 v4, v10, v0
	v_pk_mul_f32 v[4:5], v[0:1], v[4:5] op_sel:[1,0]
	v_pk_mul_f32 v[0:1], v[0:1], v[2:3] op_sel:[1,0]
	v_pk_fma_f32 v[2:3], v[206:207], v[4:5], v[210:211]
	v_pk_fma_f32 v[0:1], v[204:205], v[0:1], v[208:209]
	v_mov_b32_e32 v4, 0x7fc00000
	v_cndmask_b32_e64 v3, v4, v3, s[4:5]
	v_cndmask_b32_e64 v2, v4, v2, s[4:5]
	v_cndmask_b32_e64 v1, v4, v1, s[4:5]
	v_cndmask_b32_e64 v0, v4, v0, s[4:5]
	global_store_dwordx4 v[120:121], v[0:3], off offset:576 sc1
	s_cbranch_vccnz .LBB0_1069
	v_lshl_add_u64 v[6:7], v[124:125], 0, v[40:41]
	v_cvt_pk_bf16_f32 v0, v0, v1
	v_cvt_pk_bf16_f32 v1, v2, v3
	v_lshl_add_u64 v[2:3], v[6:7], 1, s[34:35]
	global_store_dwordx2 v[2:3], v[0:1], off sc1
.LBB0_1069:
	ds_read_b64 v[0:1], v152 offset:8576
	s_and_b64 vcc, exec, s[6:7]
	s_waitcnt lgkmcnt(0)
	v_sub_f32_e32 v3, v13, v0
	v_sub_f32_e32 v2, v12, v0
	v_sub_f32_e32 v7, v15, v0
	v_sub_f32_e32 v6, v14, v0
	v_pk_mul_f32 v[6:7], v[0:1], v[6:7] op_sel:[1,0]
	v_pk_mul_f32 v[0:1], v[0:1], v[2:3] op_sel:[1,0]
	v_pk_fma_f32 v[2:3], v[206:207], v[6:7], v[210:211]
	v_pk_fma_f32 v[0:1], v[204:205], v[0:1], v[208:209]
	v_cndmask_b32_e64 v3, v4, v3, s[4:5]
	v_cndmask_b32_e64 v2, v4, v2, s[4:5]
	v_cndmask_b32_e64 v1, v4, v1, s[4:5]
	v_cndmask_b32_e64 v0, v4, v0, s[4:5]
	global_store_dwordx4 v[118:119], v[0:3], off offset:576 sc1
	s_cbranch_vccnz .LBB0_1071
	v_lshl_add_u64 v[4:5], v[116:117], 0, v[40:41]
	v_cvt_pk_bf16_f32 v0, v0, v1
	v_cvt_pk_bf16_f32 v1, v2, v3
	v_lshl_add_u64 v[2:3], v[4:5], 1, s[34:35]
	global_store_dwordx2 v[2:3], v[0:1], off sc1
.LBB0_1071:
	ds_read_b64 v[0:1], v152 offset:9216
	s_and_b64 vcc, exec, s[6:7]
	s_waitcnt lgkmcnt(0)
	v_sub_f32_e32 v3, v17, v0
	v_sub_f32_e32 v2, v16, v0
	v_sub_f32_e32 v5, v19, v0
	v_sub_f32_e32 v4, v18, v0
	v_pk_mul_f32 v[4:5], v[0:1], v[4:5] op_sel:[1,0]
	v_pk_mul_f32 v[0:1], v[0:1], v[2:3] op_sel:[1,0]
	v_pk_fma_f32 v[2:3], v[206:207], v[4:5], v[210:211]
	v_pk_fma_f32 v[0:1], v[204:205], v[0:1], v[208:209]
	v_mov_b32_e32 v4, 0x7fc00000
	v_cndmask_b32_e64 v3, v4, v3, s[4:5]
	v_cndmask_b32_e64 v2, v4, v2, s[4:5]
	v_cndmask_b32_e64 v1, v4, v1, s[4:5]
	v_cndmask_b32_e64 v0, v4, v0, s[4:5]
	global_store_dwordx4 v[114:115], v[0:3], off offset:576 sc1
	s_cbranch_vccnz .LBB0_1073
	v_lshl_add_u64 v[6:7], v[112:113], 0, v[40:41]
	v_cvt_pk_bf16_f32 v0, v0, v1
	v_cvt_pk_bf16_f32 v1, v2, v3
	v_lshl_add_u64 v[2:3], v[6:7], 1, s[34:35]
	global_store_dwordx2 v[2:3], v[0:1], off sc1
.LBB0_1073:
	ds_read_b64 v[0:1], v152 offset:9344
	s_and_b64 vcc, exec, s[6:7]
	s_waitcnt lgkmcnt(0)
	v_sub_f32_e32 v3, v21, v0
	v_sub_f32_e32 v2, v20, v0
	v_sub_f32_e32 v7, v23, v0
	v_sub_f32_e32 v6, v22, v0
	v_pk_mul_f32 v[6:7], v[0:1], v[6:7] op_sel:[1,0]
	v_pk_mul_f32 v[0:1], v[0:1], v[2:3] op_sel:[1,0]
	v_pk_fma_f32 v[2:3], v[206:207], v[6:7], v[210:211]
	v_pk_fma_f32 v[0:1], v[204:205], v[0:1], v[208:209]
	v_cndmask_b32_e64 v3, v4, v3, s[4:5]
	v_cndmask_b32_e64 v2, v4, v2, s[4:5]
	v_cndmask_b32_e64 v1, v4, v1, s[4:5]
	v_cndmask_b32_e64 v0, v4, v0, s[4:5]
	global_store_dwordx4 v[110:111], v[0:3], off offset:576 sc1
	s_cbranch_vccnz .LBB0_1075
	v_lshl_add_u64 v[4:5], v[108:109], 0, v[40:41]
	v_cvt_pk_bf16_f32 v0, v0, v1
	v_cvt_pk_bf16_f32 v1, v2, v3
	v_lshl_add_u64 v[2:3], v[4:5], 1, s[34:35]
	global_store_dwordx2 v[2:3], v[0:1], off sc1
.LBB0_1075:
	ds_read_b64 v[0:1], v152 offset:9472
	s_and_b64 vcc, exec, s[6:7]
	s_waitcnt lgkmcnt(0)
	v_sub_f32_e32 v3, v25, v0
	v_sub_f32_e32 v2, v24, v0
	v_sub_f32_e32 v5, v27, v0
	v_sub_f32_e32 v4, v26, v0
	v_pk_mul_f32 v[4:5], v[0:1], v[4:5] op_sel:[1,0]
	v_pk_mul_f32 v[0:1], v[0:1], v[2:3] op_sel:[1,0]
	v_pk_fma_f32 v[2:3], v[206:207], v[4:5], v[210:211]
	v_pk_fma_f32 v[0:1], v[204:205], v[0:1], v[208:209]
	v_mov_b32_e32 v4, 0x7fc00000
	v_cndmask_b32_e64 v3, v4, v3, s[4:5]
	v_cndmask_b32_e64 v2, v4, v2, s[4:5]
	v_cndmask_b32_e64 v1, v4, v1, s[4:5]
	v_cndmask_b32_e64 v0, v4, v0, s[4:5]
	global_store_dwordx4 v[122:123], v[0:3], off offset:576 sc1
	s_cbranch_vccnz .LBB0_1077
	v_lshl_add_u64 v[6:7], v[92:93], 0, v[40:41]
	v_cvt_pk_bf16_f32 v0, v0, v1
	v_cvt_pk_bf16_f32 v1, v2, v3
	v_lshl_add_u64 v[2:3], v[6:7], 1, s[34:35]
	global_store_dwordx2 v[2:3], v[0:1], off sc1
.LBB0_1077:
	ds_read_b64 v[0:1], v152 offset:9600
	s_and_b64 vcc, exec, s[6:7]
	s_waitcnt lgkmcnt(0)
	v_sub_f32_e32 v3, v33, v0
	v_sub_f32_e32 v2, v32, v0
	v_sub_f32_e32 v7, v35, v0
	v_sub_f32_e32 v6, v34, v0
	v_pk_mul_f32 v[6:7], v[0:1], v[6:7] op_sel:[1,0]
	v_pk_mul_f32 v[0:1], v[0:1], v[2:3] op_sel:[1,0]
	v_pk_fma_f32 v[2:3], v[206:207], v[6:7], v[210:211]
	v_pk_fma_f32 v[0:1], v[204:205], v[0:1], v[208:209]
	v_cndmask_b32_e64 v3, v4, v3, s[4:5]
	v_cndmask_b32_e64 v2, v4, v2, s[4:5]
	v_cndmask_b32_e64 v1, v4, v1, s[4:5]
	v_cndmask_b32_e64 v0, v4, v0, s[4:5]
	global_store_dwordx4 v[128:129], v[0:3], off offset:576 sc1
	s_cbranch_vccnz .LBB0_1079
	v_lshl_add_u64 v[4:5], v[94:95], 0, v[40:41]
	v_cvt_pk_bf16_f32 v0, v0, v1
	v_cvt_pk_bf16_f32 v1, v2, v3
	v_lshl_add_u64 v[2:3], v[4:5], 1, s[34:35]
	global_store_dwordx2 v[2:3], v[0:1], off sc1

.LBB0_1272:
	s_or_b64 exec, exec, s[6:7]
	s_waitcnt lgkmcnt(0)
	s_barrier
	v_lshl_add_u64 v[154:155], s[12:13], 0, v[132:133]
	v_lshl_add_u64 v[156:157], s[14:15], 0, v[132:133]
	global_load_dwordx4 v[128:131], v[154:155], off
	global_load_dwordx4 v[132:135], v[156:157], off
	v_or_b32_e32 v158, s0, v158
	v_lshl_add_u32 v167, v158, 3, 0
	ds_read_b64 v[160:161], v167 offset:8192
	v_mov_b32_e32 v166, 0x7fc00000
	s_waitcnt lgkmcnt(1)
	v_cmp_eq_u32_e32 vcc, 0, v159
	v_add_u32_e32 v164, s20, v158
	v_ashrrev_i32_e32 v165, 31, v164
	s_waitcnt lgkmcnt(0)
	v_sub_f32_e32 v113, v113, v160
	v_sub_f32_e32 v112, v112, v160
	v_sub_f32_e32 v115, v115, v160
	v_sub_f32_e32 v114, v114, v160
	v_pk_mul_f32 v[114:115], v[160:161], v[114:115] op_sel:[1,0]
	v_pk_mul_f32 v[112:113], v[160:161], v[112:113] op_sel:[1,0]
	s_add_u32 s4, s18, 0x7200000
	v_add_u32_e32 v168, 16, v164
	v_lshlrev_b64 v[162:163], 10, v[164:165]
	s_addc_u32 s5, s19, 0
	v_ashrrev_i32_e32 v169, 31, v168
	v_lshl_add_u64 v[176:177], v[162:163], 0, v[136:137]
	v_lshlrev_b64 v[160:161], 10, v[168:169]
	v_lshl_add_u64 v[168:169], v[176:177], 1, s[4:5]
	v_add_u32_e32 v170, 32, v164
	v_ashrrev_i32_e32 v171, 31, v170
	v_lshlrev_b64 v[158:159], 10, v[170:171]
	v_add_u32_e32 v172, 48, v164
	v_add_u32_e32 v174, 0x80, v164
	v_ashrrev_i32_e32 v173, 31, v172
	v_ashrrev_i32_e32 v175, 31, v174
	s_mov_b64 s[0:1], 0x80
	global_load_dwordx4 v[188:191], v[154:155], off offset:64
	global_load_dwordx4 v[192:195], v[156:157], off offset:64
	global_load_dwordx4 v[196:199], v[154:155], off offset:512
	global_load_dwordx4 v[200:203], v[156:157], off offset:512
	global_load_dwordx4 v[204:207], v[154:155], off offset:576
	global_load_dwordx4 v[208:211], v[156:157], off offset:576
	s_waitcnt vmcnt(0)
	v_pk_fma_f32 v[112:113], v[128:129], v[112:113], v[132:133]
	v_pk_fma_f32 v[114:115], v[130:131], v[114:115], v[134:135]
	v_cndmask_b32_e32 v113, v166, v113, vcc
	v_cndmask_b32_e32 v115, v166, v115, vcc
	v_cndmask_b32_e32 v114, v166, v114, vcc
	v_cndmask_b32_e32 v112, v166, v112, vcc
	global_store_dwordx4 v[138:139], v[112:115], off sc1
	s_nop 1
	v_cvt_pk_bf16_f32 v112, v112, v113
	v_cvt_pk_bf16_f32 v113, v114, v115
	ds_read_b64 v[114:115], v167 offset:8320
	global_store_dwordx2 v[168:169], v[112:113], off sc1
	s_waitcnt lgkmcnt(0)
	v_sub_f32_e32 v113, v121, v114
	v_sub_f32_e32 v112, v120, v114
	v_sub_f32_e32 v121, v123, v114
	v_sub_f32_e32 v120, v122, v114
	v_pk_mul_f32 v[120:121], v[114:115], v[120:121] op_sel:[1,0]
	v_pk_mul_f32 v[112:113], v[114:115], v[112:113] op_sel:[1,0]
	v_pk_fma_f32 v[114:115], v[130:131], v[120:121], v[134:135]
	v_pk_fma_f32 v[112:113], v[128:129], v[112:113], v[132:133]
	v_cndmask_b32_e32 v115, v166, v115, vcc
	v_cndmask_b32_e32 v114, v166, v114, vcc
	v_cndmask_b32_e32 v113, v166, v113, vcc
	v_cndmask_b32_e32 v112, v166, v112, vcc
	global_store_dwordx4 v[140:141], v[112:115], off sc1
	v_lshl_add_u64 v[122:123], v[160:161], 0, v[136:137]
	v_lshl_add_u64 v[122:123], v[122:123], 1, s[4:5]
	v_cvt_pk_bf16_f32 v112, v112, v113
	v_cvt_pk_bf16_f32 v113, v114, v115
	ds_read_b64 v[120:121], v167 offset:8448
	global_store_dwordx2 v[122:123], v[112:113], off sc1
	v_lshlrev_b64 v[114:115], 10, v[172:173]
	s_waitcnt lgkmcnt(0)
	v_sub_f32_e32 v113, v125, v120
	v_sub_f32_e32 v112, v124, v120
	v_sub_f32_e32 v123, v127, v120
	v_sub_f32_e32 v122, v126, v120
	v_pk_mul_f32 v[122:123], v[120:121], v[122:123] op_sel:[1,0]
	v_pk_mul_f32 v[112:113], v[120:121], v[112:113] op_sel:[1,0]
	v_pk_fma_f32 v[120:121], v[130:131], v[122:123], v[134:135]
	v_pk_fma_f32 v[112:113], v[128:129], v[112:113], v[132:133]
	v_cndmask_b32_e32 v123, v166, v121, vcc
	v_cndmask_b32_e32 v122, v166, v120, vcc
	v_cndmask_b32_e32 v121, v166, v113, vcc
	v_cndmask_b32_e32 v120, v166, v112, vcc
	global_store_dwordx4 v[142:143], v[120:123], off sc1
	v_lshl_add_u64 v[124:125], v[158:159], 0, v[136:137]
	v_lshl_add_u64 v[124:125], v[124:125], 1, s[4:5]
	v_cvt_pk_bf16_f32 v120, v120, v121
	v_cvt_pk_bf16_f32 v121, v122, v123
	ds_read_b64 v[122:123], v167 offset:8576
	global_store_dwordx2 v[124:125], v[120:121], off sc1
	v_lshlrev_b64 v[112:113], 10, v[174:175]
	v_lshl_add_u64 v[120:121], v[114:115], 0, v[136:137]
	v_lshl_add_u64 v[120:121], v[120:121], 1, s[4:5]
	s_waitcnt lgkmcnt(0)
	v_sub_f32_e32 v117, v117, v122
	v_sub_f32_e32 v116, v116, v122
	v_sub_f32_e32 v119, v119, v122
	v_sub_f32_e32 v118, v118, v122
	v_pk_mul_f32 v[118:119], v[122:123], v[118:119] op_sel:[1,0]
	v_pk_mul_f32 v[116:117], v[122:123], v[116:117] op_sel:[1,0]
	v_pk_fma_f32 v[118:119], v[130:131], v[118:119], v[134:135]
	v_pk_fma_f32 v[116:117], v[128:129], v[116:117], v[132:133]
	v_cndmask_b32_e32 v119, v166, v119, vcc
	v_cndmask_b32_e32 v118, v166, v118, vcc
	v_cndmask_b32_e32 v117, v166, v117, vcc
	v_cndmask_b32_e32 v116, v166, v116, vcc
	global_store_dwordx4 v[144:145], v[116:119], off sc1
	v_lshl_add_u64 v[122:123], v[112:113], 0, v[136:137]
	s_nop 0
	v_cvt_pk_bf16_f32 v116, v116, v117
	v_cvt_pk_bf16_f32 v117, v118, v119
	ds_read_b64 v[118:119], v167 offset:9216
	global_store_dwordx2 v[120:121], v[116:117], off sc1
	s_waitcnt lgkmcnt(0)
	v_sub_f32_e32 v105, v105, v118
	v_sub_f32_e32 v104, v104, v118
	v_sub_f32_e32 v107, v107, v118
	v_sub_f32_e32 v106, v106, v118
	v_pk_mul_f32 v[106:107], v[118:119], v[106:107] op_sel:[1,0]
	v_pk_mul_f32 v[104:105], v[118:119], v[104:105] op_sel:[1,0]
	v_pk_fma_f32 v[106:107], v[130:131], v[106:107], v[134:135]
	v_pk_fma_f32 v[104:105], v[128:129], v[104:105], v[132:133]
	v_cndmask_b32_e32 v107, v166, v107, vcc
	v_cndmask_b32_e32 v106, v166, v106, vcc
	v_cndmask_b32_e32 v105, v166, v105, vcc
	v_cndmask_b32_e32 v104, v166, v104, vcc
	global_store_dwordx4 v[146:147], v[104:107], off sc1
	s_nop 1
	v_cvt_pk_bf16_f32 v104, v104, v105
	v_cvt_pk_bf16_f32 v105, v106, v107
	v_lshl_add_u64 v[106:107], v[122:123], 1, s[4:5]
	global_store_dwordx2 v[106:107], v[104:105], off sc1
	ds_read_b64 v[106:107], v167 offset:9344
	v_add_u32_e32 v104, 0x90, v164
	v_ashrrev_i32_e32 v105, 31, v104
	v_lshlrev_b64 v[104:105], 10, v[104:105]
	v_lshl_add_u64 v[116:117], v[104:105], 0, v[136:137]
	s_waitcnt lgkmcnt(0)
	v_sub_f32_e32 v89, v89, v106
	v_sub_f32_e32 v88, v88, v106
	v_sub_f32_e32 v91, v91, v106
	v_sub_f32_e32 v90, v90, v106
	v_pk_mul_f32 v[90:91], v[106:107], v[90:91] op_sel:[1,0]
	v_pk_mul_f32 v[88:89], v[106:107], v[88:89] op_sel:[1,0]
	v_pk_fma_f32 v[90:91], v[130:131], v[90:91], v[134:135]
	v_pk_fma_f32 v[88:89], v[128:129], v[88:89], v[132:133]
	v_cndmask_b32_e32 v91, v166, v91, vcc
	v_cndmask_b32_e32 v90, v166, v90, vcc
	v_cndmask_b32_e32 v89, v166, v89, vcc
	v_cndmask_b32_e32 v88, v166, v88, vcc
	global_store_dwordx4 v[148:149], v[88:91], off sc1
	s_nop 1
	v_cvt_pk_bf16_f32 v88, v88, v89
	v_cvt_pk_bf16_f32 v89, v90, v91
	v_lshl_add_u64 v[90:91], v[116:117], 1, s[4:5]
	global_store_dwordx2 v[90:91], v[88:89], off sc1
	ds_read_b64 v[90:91], v167 offset:9472
	v_add_u32_e32 v88, 0xa0, v164
	v_ashrrev_i32_e32 v89, 31, v88
	v_lshlrev_b64 v[88:89], 10, v[88:89]
	v_lshl_add_u64 v[106:107], v[88:89], 0, v[136:137]
	s_waitcnt lgkmcnt(0)
	v_sub_f32_e32 v65, v65, v90
	v_sub_f32_e32 v64, v64, v90
	v_sub_f32_e32 v67, v67, v90
	v_sub_f32_e32 v66, v66, v90
	v_pk_mul_f32 v[66:67], v[90:91], v[66:67] op_sel:[1,0]
	v_pk_mul_f32 v[64:65], v[90:91], v[64:65] op_sel:[1,0]
	v_pk_fma_f32 v[66:67], v[130:131], v[66:67], v[134:135]
	v_pk_fma_f32 v[64:65], v[128:129], v[64:65], v[132:133]
	v_cndmask_b32_e32 v67, v166, v67, vcc
	v_cndmask_b32_e32 v66, v166, v66, vcc
	v_cndmask_b32_e32 v65, v166, v65, vcc
	v_cndmask_b32_e32 v64, v166, v64, vcc
	global_store_dwordx4 v[150:151], v[64:67], off sc1
	s_nop 1
	v_cvt_pk_bf16_f32 v64, v64, v65
	v_cvt_pk_bf16_f32 v65, v66, v67
	v_lshl_add_u64 v[66:67], v[106:107], 1, s[4:5]
	global_store_dwordx2 v[66:67], v[64:65], off sc1
	ds_read_b64 v[66:67], v167 offset:9600
	v_add_u32_e32 v64, 0xb0, v164
	v_ashrrev_i32_e32 v65, 31, v64
	v_lshlrev_b64 v[64:65], 10, v[64:65]
	v_lshl_add_u64 v[90:91], v[64:65], 0, v[136:137]
	s_waitcnt lgkmcnt(0)
	v_sub_f32_e32 v37, v37, v66
	v_sub_f32_e32 v36, v36, v66
	v_sub_f32_e32 v39, v39, v66
	v_sub_f32_e32 v38, v38, v66
	v_pk_mul_f32 v[38:39], v[66:67], v[38:39] op_sel:[1,0]
	v_pk_mul_f32 v[36:37], v[66:67], v[36:37] op_sel:[1,0]
	v_pk_fma_f32 v[38:39], v[130:131], v[38:39], v[134:135]
	v_pk_fma_f32 v[36:37], v[128:129], v[36:37], v[132:133]
	v_cndmask_b32_e32 v39, v166, v39, vcc
	v_cndmask_b32_e32 v38, v166, v38, vcc
	v_cndmask_b32_e32 v37, v166, v37, vcc
	v_cndmask_b32_e32 v36, v166, v36, vcc
	global_store_dwordx4 v[152:153], v[36:39], off sc1
	s_nop 1
	v_cvt_pk_bf16_f32 v36, v36, v37
	v_cvt_pk_bf16_f32 v37, v38, v39
	v_lshl_add_u64 v[38:39], v[90:91], 1, s[4:5]
	global_store_dwordx2 v[38:39], v[36:37], off sc1
	ds_read_b64 v[66:67], v167 offset:8192
	v_lshl_add_u64 v[90:91], v[136:137], 0, 16
	s_waitcnt lgkmcnt(0)
	v_sub_f32_e32 v85, v85, v66
	v_sub_f32_e32 v84, v84, v66
	v_sub_f32_e32 v87, v87, v66
	v_sub_f32_e32 v86, v86, v66
	v_pk_mul_f32 v[86:87], v[66:67], v[86:87] op_sel:[1,0]
	v_pk_mul_f32 v[66:67], v[66:67], v[84:85] op_sel:[1,0]
	v_pk_fma_f32 v[84:85], v[190:191], v[86:87], v[194:195]
	v_pk_fma_f32 v[66:67], v[188:189], v[66:67], v[192:193]
	v_cndmask_b32_e32 v87, v166, v85, vcc
	v_cndmask_b32_e32 v86, v166, v84, vcc
	v_cndmask_b32_e32 v85, v166, v67, vcc
	v_cndmask_b32_e32 v84, v166, v66, vcc
	global_store_dwordx4 v[138:139], v[84:87], off offset:64 sc1
	v_cvt_pk_bf16_f32 v66, v84, v85
	v_cvt_pk_bf16_f32 v67, v86, v87
	ds_read_b64 v[84:85], v167 offset:8320
	s_nop 0
	v_lshl_add_u64 v[86:87], v[162:163], 0, v[90:91]
	v_lshl_add_u64 v[86:87], v[86:87], 1, s[4:5]
	global_store_dwordx2 v[86:87], v[66:67], off sc1
	s_waitcnt lgkmcnt(0)
	v_sub_f32_e32 v67, v93, v84
	v_sub_f32_e32 v66, v92, v84
	v_sub_f32_e32 v87, v95, v84
	v_sub_f32_e32 v86, v94, v84
	v_pk_mul_f32 v[86:87], v[84:85], v[86:87] op_sel:[1,0]
	v_pk_mul_f32 v[66:67], v[84:85], v[66:67] op_sel:[1,0]
	v_pk_fma_f32 v[84:85], v[190:191], v[86:87], v[194:195]
	v_pk_fma_f32 v[66:67], v[188:189], v[66:67], v[192:193]
	v_cndmask_b32_e32 v87, v166, v85, vcc
	v_cndmask_b32_e32 v86, v166, v84, vcc
	v_cndmask_b32_e32 v85, v166, v67, vcc
	v_cndmask_b32_e32 v84, v166, v66, vcc
	global_store_dwordx4 v[140:141], v[84:87], off offset:64 sc1
	v_cvt_pk_bf16_f32 v66, v84, v85
	v_cvt_pk_bf16_f32 v67, v86, v87
	ds_read_b64 v[84:85], v167 offset:8448
	s_nop 0
	v_lshl_add_u64 v[86:87], v[160:161], 0, v[90:91]
	v_lshl_add_u64 v[86:87], v[86:87], 1, s[4:5]
	global_store_dwordx2 v[86:87], v[66:67], off sc1
	s_waitcnt lgkmcnt(0)
	v_sub_f32_e32 v67, v97, v84
	v_sub_f32_e32 v66, v96, v84
	v_sub_f32_e32 v87, v99, v84
	v_sub_f32_e32 v86, v98, v84
	v_pk_mul_f32 v[86:87], v[84:85], v[86:87] op_sel:[1,0]
	v_pk_mul_f32 v[66:67], v[84:85], v[66:67] op_sel:[1,0]
	v_pk_fma_f32 v[84:85], v[190:191], v[86:87], v[194:195]
	v_pk_fma_f32 v[66:67], v[188:189], v[66:67], v[192:193]
	v_cndmask_b32_e32 v87, v166, v85, vcc
	v_cndmask_b32_e32 v86, v166, v84, vcc
	v_cndmask_b32_e32 v85, v166, v67, vcc
	v_cndmask_b32_e32 v84, v166, v66, vcc
	global_store_dwordx4 v[142:143], v[84:87], off offset:64 sc1
	v_cvt_pk_bf16_f32 v66, v84, v85
	v_cvt_pk_bf16_f32 v67, v86, v87
	ds_read_b64 v[84:85], v167 offset:8576
	s_nop 0
	v_lshl_add_u64 v[86:87], v[158:159], 0, v[90:91]
	v_lshl_add_u64 v[86:87], v[86:87], 1, s[4:5]
	global_store_dwordx2 v[86:87], v[66:67], off sc1
	s_waitcnt lgkmcnt(0)
	v_sub_f32_e32 v67, v109, v84
	v_sub_f32_e32 v66, v108, v84
	v_sub_f32_e32 v87, v111, v84
	v_sub_f32_e32 v86, v110, v84
	v_pk_mul_f32 v[86:87], v[84:85], v[86:87] op_sel:[1,0]
	v_pk_mul_f32 v[66:67], v[84:85], v[66:67] op_sel:[1,0]
	v_pk_fma_f32 v[84:85], v[190:191], v[86:87], v[194:195]
	v_pk_fma_f32 v[66:67], v[188:189], v[66:67], v[192:193]
	v_cndmask_b32_e32 v87, v166, v85, vcc
	v_cndmask_b32_e32 v86, v166, v84, vcc
	v_cndmask_b32_e32 v85, v166, v67, vcc
	v_cndmask_b32_e32 v84, v166, v66, vcc
	global_store_dwordx4 v[144:145], v[84:87], off offset:64 sc1
	v_cvt_pk_bf16_f32 v66, v84, v85
	v_cvt_pk_bf16_f32 v67, v86, v87
	ds_read_b64 v[84:85], v167 offset:9216
	s_nop 0
	v_lshl_add_u64 v[86:87], v[114:115], 0, v[90:91]
	v_lshl_add_u64 v[86:87], v[86:87], 1, s[4:5]
	global_store_dwordx2 v[86:87], v[66:67], off sc1
	s_waitcnt lgkmcnt(0)
	v_sub_f32_e32 v67, v101, v84
	v_sub_f32_e32 v66, v100, v84
	v_sub_f32_e32 v87, v103, v84
	v_sub_f32_e32 v86, v102, v84
	v_pk_mul_f32 v[86:87], v[84:85], v[86:87] op_sel:[1,0]
	v_pk_mul_f32 v[66:67], v[84:85], v[66:67] op_sel:[1,0]
	v_pk_fma_f32 v[84:85], v[190:191], v[86:87], v[194:195]
	v_pk_fma_f32 v[66:67], v[188:189], v[66:67], v[192:193]
	v_cndmask_b32_e32 v87, v166, v85, vcc
	v_cndmask_b32_e32 v86, v166, v84, vcc
	v_cndmask_b32_e32 v85, v166, v67, vcc
	v_cndmask_b32_e32 v84, v166, v66, vcc
	global_store_dwordx4 v[146:147], v[84:87], off offset:64 sc1
	v_cvt_pk_bf16_f32 v66, v84, v85
	v_cvt_pk_bf16_f32 v67, v86, v87
	ds_read_b64 v[84:85], v167 offset:9344
	s_nop 0
	v_lshl_add_u64 v[86:87], v[112:113], 0, v[90:91]
	v_lshl_add_u64 v[86:87], v[86:87], 1, s[4:5]
	global_store_dwordx2 v[86:87], v[66:67], off sc1
	s_waitcnt lgkmcnt(0)
	v_sub_f32_e32 v67, v81, v84
	v_sub_f32_e32 v66, v80, v84
	v_sub_f32_e32 v81, v83, v84
	v_sub_f32_e32 v80, v82, v84
	v_pk_mul_f32 v[80:81], v[84:85], v[80:81] op_sel:[1,0]
	v_pk_mul_f32 v[66:67], v[84:85], v[66:67] op_sel:[1,0]
	v_pk_fma_f32 v[80:81], v[190:191], v[80:81], v[194:195]
	v_pk_fma_f32 v[66:67], v[188:189], v[66:67], v[192:193]
	v_cndmask_b32_e32 v83, v166, v81, vcc
	v_cndmask_b32_e32 v82, v166, v80, vcc
	v_cndmask_b32_e32 v81, v166, v67, vcc
	v_cndmask_b32_e32 v80, v166, v66, vcc
	global_store_dwordx4 v[148:149], v[80:83], off offset:64 sc1
	v_cvt_pk_bf16_f32 v66, v80, v81
	v_cvt_pk_bf16_f32 v67, v82, v83
	ds_read_b64 v[80:81], v167 offset:9472
	s_waitcnt lgkmcnt(0)
	v_sub_f32_e32 v61, v61, v80
	v_sub_f32_e32 v60, v60, v80
	v_sub_f32_e32 v63, v63, v80
	v_sub_f32_e32 v62, v62, v80
	v_pk_mul_f32 v[62:63], v[80:81], v[62:63] op_sel:[1,0]
	v_pk_mul_f32 v[60:61], v[80:81], v[60:61] op_sel:[1,0]
	v_lshl_add_u64 v[82:83], v[104:105], 0, v[90:91]
	v_pk_fma_f32 v[60:61], v[188:189], v[60:61], v[192:193]
	v_pk_fma_f32 v[62:63], v[190:191], v[62:63], v[194:195]
	v_lshl_add_u64 v[82:83], v[82:83], 1, s[4:5]
	v_cndmask_b32_e32 v63, v166, v63, vcc
	v_cndmask_b32_e32 v62, v166, v62, vcc
	v_cndmask_b32_e32 v61, v166, v61, vcc
	v_cndmask_b32_e32 v60, v166, v60, vcc
	global_store_dwordx2 v[82:83], v[66:67], off sc1
	global_store_dwordx4 v[150:151], v[60:63], off offset:64 sc1
	v_lshl_add_u64 v[66:67], v[88:89], 0, v[90:91]
	v_lshl_add_u64 v[66:67], v[66:67], 1, s[4:5]
	v_cvt_pk_bf16_f32 v60, v60, v61
	v_cvt_pk_bf16_f32 v61, v62, v63
	ds_read_b64 v[62:63], v167 offset:9600
	global_store_dwordx2 v[66:67], v[60:61], off sc1
	v_lshl_add_u64 v[60:61], v[64:65], 0, v[90:91]
	s_waitcnt lgkmcnt(0)
	v_sub_f32_e32 v33, v33, v62
	v_sub_f32_e32 v32, v32, v62
	v_sub_f32_e32 v35, v35, v62
	v_sub_f32_e32 v34, v34, v62
	v_pk_mul_f32 v[34:35], v[62:63], v[34:35] op_sel:[1,0]
	v_pk_mul_f32 v[32:33], v[62:63], v[32:33] op_sel:[1,0]
	v_pk_fma_f32 v[34:35], v[190:191], v[34:35], v[194:195]
	v_pk_fma_f32 v[32:33], v[188:189], v[32:33], v[192:193]
	v_cndmask_b32_e32 v35, v166, v35, vcc
	v_cndmask_b32_e32 v34, v166, v34, vcc
	v_cndmask_b32_e32 v33, v166, v33, vcc
	v_cndmask_b32_e32 v32, v166, v32, vcc
	global_store_dwordx4 v[152:153], v[32:35], off offset:64 sc1
	s_nop 1
	v_cvt_pk_bf16_f32 v32, v32, v33
	v_cvt_pk_bf16_f32 v33, v34, v35
	v_lshl_add_u64 v[34:35], v[60:61], 1, s[4:5]
	global_store_dwordx2 v[34:35], v[32:33], off sc1
	ds_read_b64 v[60:61], v167 offset:8192
	s_waitcnt lgkmcnt(0)
	v_sub_f32_e32 v41, v41, v60
	v_sub_f32_e32 v40, v40, v60
	v_sub_f32_e32 v43, v43, v60
	v_sub_f32_e32 v42, v42, v60
	v_pk_mul_f32 v[42:43], v[60:61], v[42:43] op_sel:[1,0]
	v_pk_mul_f32 v[40:41], v[60:61], v[40:41] op_sel:[1,0]
	v_lshl_add_u64 v[60:61], v[136:137], 0, s[0:1]
	v_lshl_add_u64 v[62:63], v[162:163], 0, v[60:61]
	v_lshl_add_u64 v[62:63], v[62:63], 1, s[4:5]
	s_mov_b64 s[0:1], 0x90
	v_pk_fma_f32 v[40:41], v[196:197], v[40:41], v[200:201]
	v_pk_fma_f32 v[42:43], v[198:199], v[42:43], v[202:203]
	v_cndmask_b32_e32 v41, v166, v41, vcc
	v_cndmask_b32_e32 v43, v166, v43, vcc
	v_cndmask_b32_e32 v42, v166, v42, vcc
	v_cndmask_b32_e32 v40, v166, v40, vcc
	global_store_dwordx4 v[138:139], v[40:43], off offset:512 sc1
	s_nop 1
	v_cvt_pk_bf16_f32 v40, v40, v41
	v_cvt_pk_bf16_f32 v41, v42, v43
	ds_read_b64 v[42:43], v167 offset:8320
	global_store_dwordx2 v[62:63], v[40:41], off sc1
	s_waitcnt lgkmcnt(0)
	v_sub_f32_e32 v41, v53, v42
	v_sub_f32_e32 v40, v52, v42
	v_sub_f32_e32 v53, v55, v42
	v_sub_f32_e32 v52, v54, v42
	v_pk_mul_f32 v[52:53], v[42:43], v[52:53] op_sel:[1,0]
	v_pk_mul_f32 v[40:41], v[42:43], v[40:41] op_sel:[1,0]
	v_pk_fma_f32 v[42:43], v[198:199], v[52:53], v[202:203]
	v_pk_fma_f32 v[40:41], v[196:197], v[40:41], v[200:201]
	v_cndmask_b32_e32 v43, v166, v43, vcc
	v_cndmask_b32_e32 v42, v166, v42, vcc
	v_cndmask_b32_e32 v41, v166, v41, vcc
	v_cndmask_b32_e32 v40, v166, v40, vcc
	global_store_dwordx4 v[140:141], v[40:43], off offset:512 sc1
	v_lshl_add_u64 v[52:53], v[160:161], 0, v[60:61]
	v_lshl_add_u64 v[52:53], v[52:53], 1, s[4:5]
	v_cvt_pk_bf16_f32 v40, v40, v41
	v_cvt_pk_bf16_f32 v41, v42, v43
	ds_read_b64 v[42:43], v167 offset:8448
	global_store_dwordx2 v[52:53], v[40:41], off sc1
	s_waitcnt lgkmcnt(0)
	v_sub_f32_e32 v41, v57, v42
	v_sub_f32_e32 v40, v56, v42
	v_sub_f32_e32 v53, v59, v42
	v_sub_f32_e32 v52, v58, v42
	v_pk_mul_f32 v[52:53], v[42:43], v[52:53] op_sel:[1,0]
	v_pk_mul_f32 v[40:41], v[42:43], v[40:41] op_sel:[1,0]
	v_pk_fma_f32 v[42:43], v[198:199], v[52:53], v[202:203]
	v_pk_fma_f32 v[40:41], v[196:197], v[40:41], v[200:201]
	v_cndmask_b32_e32 v43, v166, v43, vcc
	v_cndmask_b32_e32 v42, v166, v42, vcc
	v_cndmask_b32_e32 v41, v166, v41, vcc
	v_cndmask_b32_e32 v40, v166, v40, vcc
	global_store_dwordx4 v[142:143], v[40:43], off offset:512 sc1
	v_lshl_add_u64 v[52:53], v[158:159], 0, v[60:61]
	v_lshl_add_u64 v[52:53], v[52:53], 1, s[4:5]
	v_cvt_pk_bf16_f32 v40, v40, v41
	v_cvt_pk_bf16_f32 v41, v42, v43
	ds_read_b64 v[42:43], v167 offset:8576
	global_store_dwordx2 v[52:53], v[40:41], off sc1
	s_waitcnt lgkmcnt(0)
	v_sub_f32_e32 v41, v69, v42
	v_sub_f32_e32 v40, v68, v42
	v_sub_f32_e32 v53, v71, v42
	v_sub_f32_e32 v52, v70, v42
	v_pk_mul_f32 v[52:53], v[42:43], v[52:53] op_sel:[1,0]
	v_pk_mul_f32 v[40:41], v[42:43], v[40:41] op_sel:[1,0]
	v_pk_fma_f32 v[42:43], v[198:199], v[52:53], v[202:203]
	v_pk_fma_f32 v[40:41], v[196:197], v[40:41], v[200:201]
	v_cndmask_b32_e32 v43, v166, v43, vcc
	v_cndmask_b32_e32 v42, v166, v42, vcc
	v_cndmask_b32_e32 v41, v166, v41, vcc
	v_cndmask_b32_e32 v40, v166, v40, vcc
	global_store_dwordx4 v[144:145], v[40:43], off offset:512 sc1
	v_lshl_add_u64 v[52:53], v[114:115], 0, v[60:61]
	v_lshl_add_u64 v[52:53], v[52:53], 1, s[4:5]
	v_cvt_pk_bf16_f32 v40, v40, v41
	v_cvt_pk_bf16_f32 v41, v42, v43
	ds_read_b64 v[42:43], v167 offset:9216
	global_store_dwordx2 v[52:53], v[40:41], off sc1
	s_waitcnt lgkmcnt(0)
	v_sub_f32_e32 v41, v73, v42
	v_sub_f32_e32 v40, v72, v42
	v_sub_f32_e32 v53, v75, v42
	v_sub_f32_e32 v52, v74, v42
	v_pk_mul_f32 v[52:53], v[42:43], v[52:53] op_sel:[1,0]
	v_pk_mul_f32 v[40:41], v[42:43], v[40:41] op_sel:[1,0]
	v_pk_fma_f32 v[42:43], v[198:199], v[52:53], v[202:203]
	v_pk_fma_f32 v[40:41], v[196:197], v[40:41], v[200:201]
	v_cndmask_b32_e32 v43, v166, v43, vcc
	v_cndmask_b32_e32 v42, v166, v42, vcc
	v_cndmask_b32_e32 v41, v166, v41, vcc
	v_cndmask_b32_e32 v40, v166, v40, vcc
	global_store_dwordx4 v[146:147], v[40:43], off offset:512 sc1
	v_lshl_add_u64 v[52:53], v[112:113], 0, v[60:61]
	v_lshl_add_u64 v[52:53], v[52:53], 1, s[4:5]
	v_cvt_pk_bf16_f32 v40, v40, v41
	v_cvt_pk_bf16_f32 v41, v42, v43
	ds_read_b64 v[42:43], v167 offset:9344
	global_store_dwordx2 v[52:53], v[40:41], off sc1
	s_waitcnt lgkmcnt(0)
	v_sub_f32_e32 v41, v77, v42
	v_sub_f32_e32 v40, v76, v42
	v_sub_f32_e32 v53, v79, v42
	v_sub_f32_e32 v52, v78, v42
	v_pk_mul_f32 v[52:53], v[42:43], v[52:53] op_sel:[1,0]
	v_pk_mul_f32 v[40:41], v[42:43], v[40:41] op_sel:[1,0]
	v_pk_fma_f32 v[42:43], v[198:199], v[52:53], v[202:203]
	v_pk_fma_f32 v[40:41], v[196:197], v[40:41], v[200:201]
	v_cndmask_b32_e32 v43, v166, v43, vcc
	v_cndmask_b32_e32 v42, v166, v42, vcc
	v_cndmask_b32_e32 v41, v166, v41, vcc
	v_cndmask_b32_e32 v40, v166, v40, vcc
	global_store_dwordx4 v[148:149], v[40:43], off offset:512 sc1
	v_lshl_add_u64 v[52:53], v[104:105], 0, v[60:61]
	v_lshl_add_u64 v[52:53], v[52:53], 1, s[4:5]
	v_cvt_pk_bf16_f32 v40, v40, v41
	v_cvt_pk_bf16_f32 v41, v42, v43
	ds_read_b64 v[42:43], v167 offset:9472
	global_store_dwordx2 v[52:53], v[40:41], off sc1
	s_waitcnt lgkmcnt(0)
	v_sub_f32_e32 v41, v49, v42
	v_sub_f32_e32 v40, v48, v42
	v_sub_f32_e32 v49, v51, v42
	v_sub_f32_e32 v48, v50, v42
	v_pk_mul_f32 v[48:49], v[42:43], v[48:49] op_sel:[1,0]
	v_pk_mul_f32 v[40:41], v[42:43], v[40:41] op_sel:[1,0]
	v_pk_fma_f32 v[42:43], v[198:199], v[48:49], v[202:203]
	v_pk_fma_f32 v[40:41], v[196:197], v[40:41], v[200:201]
	v_cndmask_b32_e32 v43, v166, v43, vcc
	v_cndmask_b32_e32 v42, v166, v42, vcc
	v_cndmask_b32_e32 v41, v166, v41, vcc
	v_cndmask_b32_e32 v40, v166, v40, vcc
	global_store_dwordx4 v[150:151], v[40:43], off offset:512 sc1
	v_lshl_add_u64 v[48:49], v[88:89], 0, v[60:61]
	v_lshl_add_u64 v[48:49], v[48:49], 1, s[4:5]
	v_cvt_pk_bf16_f32 v40, v40, v41
	v_cvt_pk_bf16_f32 v41, v42, v43
	ds_read_b64 v[42:43], v167 offset:9600
	global_store_dwordx2 v[48:49], v[40:41], off sc1
	v_lshl_add_u64 v[40:41], v[64:65], 0, v[60:61]
	s_waitcnt lgkmcnt(0)
	v_sub_f32_e32 v21, v21, v42
	v_sub_f32_e32 v20, v20, v42
	v_sub_f32_e32 v23, v23, v42
	v_sub_f32_e32 v22, v22, v42
	v_pk_mul_f32 v[22:23], v[42:43], v[22:23] op_sel:[1,0]
	v_pk_mul_f32 v[20:21], v[42:43], v[20:21] op_sel:[1,0]
	v_pk_fma_f32 v[22:23], v[198:199], v[22:23], v[202:203]
	v_pk_fma_f32 v[20:21], v[196:197], v[20:21], v[200:201]
	v_cndmask_b32_e32 v23, v166, v23, vcc
	v_cndmask_b32_e32 v22, v166, v22, vcc
	v_cndmask_b32_e32 v21, v166, v21, vcc
	v_cndmask_b32_e32 v20, v166, v20, vcc
	global_store_dwordx4 v[152:153], v[20:23], off offset:512 sc1
	s_nop 1
	v_cvt_pk_bf16_f32 v20, v20, v21
	v_cvt_pk_bf16_f32 v21, v22, v23
	v_lshl_add_u64 v[22:23], v[40:41], 1, s[4:5]
	global_store_dwordx2 v[22:23], v[20:21], off sc1
	ds_read_b64 v[36:37], v167 offset:8192
	s_waitcnt lgkmcnt(0)
	v_sub_f32_e32 v1, v1, v36
	v_sub_f32_e32 v0, v0, v36
	v_sub_f32_e32 v3, v3, v36
	v_sub_f32_e32 v2, v2, v36
	v_pk_mul_f32 v[2:3], v[36:37], v[2:3] op_sel:[1,0]
	v_pk_mul_f32 v[0:1], v[36:37], v[0:1] op_sel:[1,0]
	v_lshl_add_u64 v[36:37], v[136:137], 0, s[0:1]
	v_lshl_add_u64 v[38:39], v[162:163], 0, v[36:37]
	v_lshl_add_u64 v[38:39], v[38:39], 1, s[4:5]
	v_pk_fma_f32 v[0:1], v[204:205], v[0:1], v[208:209]
	v_pk_fma_f32 v[2:3], v[206:207], v[2:3], v[210:211]
	v_cndmask_b32_e32 v1, v166, v1, vcc
	v_cndmask_b32_e32 v3, v166, v3, vcc
	v_cndmask_b32_e32 v2, v166, v2, vcc
	v_cndmask_b32_e32 v0, v166, v0, vcc
	global_store_dwordx4 v[138:139], v[0:3], off offset:576 sc1
	s_nop 1
	v_cvt_pk_bf16_f32 v0, v0, v1
	v_cvt_pk_bf16_f32 v1, v2, v3
	ds_read_b64 v[2:3], v167 offset:8320
	global_store_dwordx2 v[38:39], v[0:1], off sc1
	s_waitcnt lgkmcnt(0)
	v_sub_f32_e32 v1, v5, v2
	v_sub_f32_e32 v0, v4, v2
	v_sub_f32_e32 v5, v7, v2
	v_sub_f32_e32 v4, v6, v2
	v_pk_mul_f32 v[4:5], v[2:3], v[4:5] op_sel:[1,0]
	v_pk_mul_f32 v[0:1], v[2:3], v[0:1] op_sel:[1,0]
	v_pk_fma_f32 v[2:3], v[206:207], v[4:5], v[210:211]
	v_pk_fma_f32 v[0:1], v[204:205], v[0:1], v[208:209]
	v_cndmask_b32_e32 v3, v166, v3, vcc
	v_cndmask_b32_e32 v2, v166, v2, vcc
	v_cndmask_b32_e32 v1, v166, v1, vcc
	v_cndmask_b32_e32 v0, v166, v0, vcc
	global_store_dwordx4 v[140:141], v[0:3], off offset:576 sc1
	v_lshl_add_u64 v[4:5], v[160:161], 0, v[36:37]
	v_lshl_add_u64 v[4:5], v[4:5], 1, s[4:5]
	v_cvt_pk_bf16_f32 v0, v0, v1
	v_cvt_pk_bf16_f32 v1, v2, v3
	ds_read_b64 v[2:3], v167 offset:8448
	global_store_dwordx2 v[4:5], v[0:1], off sc1
	s_waitcnt lgkmcnt(0)
	v_sub_f32_e32 v1, v9, v2
	v_sub_f32_e32 v0, v8, v2
	v_sub_f32_e32 v5, v11, v2
	v_sub_f32_e32 v4, v10, v2
	v_pk_mul_f32 v[4:5], v[2:3], v[4:5] op_sel:[1,0]
	v_pk_mul_f32 v[0:1], v[2:3], v[0:1] op_sel:[1,0]
	v_pk_fma_f32 v[2:3], v[206:207], v[4:5], v[210:211]
	v_pk_fma_f32 v[0:1], v[204:205], v[0:1], v[208:209]
	v_cndmask_b32_e32 v3, v166, v3, vcc
	v_cndmask_b32_e32 v2, v166, v2, vcc
	v_cndmask_b32_e32 v1, v166, v1, vcc
	v_cndmask_b32_e32 v0, v166, v0, vcc
	global_store_dwordx4 v[142:143], v[0:3], off offset:576 sc1
	v_lshl_add_u64 v[4:5], v[158:159], 0, v[36:37]
	v_lshl_add_u64 v[4:5], v[4:5], 1, s[4:5]
	v_cvt_pk_bf16_f32 v0, v0, v1
	v_cvt_pk_bf16_f32 v1, v2, v3
	ds_read_b64 v[2:3], v167 offset:8576
	global_store_dwordx2 v[4:5], v[0:1], off sc1
	s_waitcnt lgkmcnt(0)
	v_sub_f32_e32 v1, v13, v2
	v_sub_f32_e32 v0, v12, v2
	v_sub_f32_e32 v5, v15, v2
	v_sub_f32_e32 v4, v14, v2
	v_pk_mul_f32 v[4:5], v[2:3], v[4:5] op_sel:[1,0]
	v_pk_mul_f32 v[0:1], v[2:3], v[0:1] op_sel:[1,0]
	v_pk_fma_f32 v[2:3], v[206:207], v[4:5], v[210:211]
	v_pk_fma_f32 v[0:1], v[204:205], v[0:1], v[208:209]
	v_cndmask_b32_e32 v3, v166, v3, vcc
	v_cndmask_b32_e32 v2, v166, v2, vcc
	v_cndmask_b32_e32 v1, v166, v1, vcc
	v_cndmask_b32_e32 v0, v166, v0, vcc
	global_store_dwordx4 v[144:145], v[0:3], off offset:576 sc1
	v_lshl_add_u64 v[4:5], v[114:115], 0, v[36:37]
	v_lshl_add_u64 v[4:5], v[4:5], 1, s[4:5]
	v_cvt_pk_bf16_f32 v0, v0, v1
	v_cvt_pk_bf16_f32 v1, v2, v3
	ds_read_b64 v[2:3], v167 offset:9216
	global_store_dwordx2 v[4:5], v[0:1], off sc1
	s_waitcnt lgkmcnt(0)
	v_sub_f32_e32 v1, v25, v2
	v_sub_f32_e32 v0, v24, v2
	v_sub_f32_e32 v5, v27, v2
	v_sub_f32_e32 v4, v26, v2
	v_pk_mul_f32 v[4:5], v[2:3], v[4:5] op_sel:[1,0]
	v_pk_mul_f32 v[0:1], v[2:3], v[0:1] op_sel:[1,0]
	v_pk_fma_f32 v[2:3], v[206:207], v[4:5], v[210:211]
	v_pk_fma_f32 v[0:1], v[204:205], v[0:1], v[208:209]
	v_cndmask_b32_e32 v3, v166, v3, vcc
	v_cndmask_b32_e32 v2, v166, v2, vcc
	v_cndmask_b32_e32 v1, v166, v1, vcc
	v_cndmask_b32_e32 v0, v166, v0, vcc
	global_store_dwordx4 v[146:147], v[0:3], off offset:576 sc1
	v_lshl_add_u64 v[4:5], v[112:113], 0, v[36:37]
	v_lshl_add_u64 v[4:5], v[4:5], 1, s[4:5]
	v_cvt_pk_bf16_f32 v0, v0, v1
	v_cvt_pk_bf16_f32 v1, v2, v3
	ds_read_b64 v[2:3], v167 offset:9344
	global_store_dwordx2 v[4:5], v[0:1], off sc1
	s_waitcnt lgkmcnt(0)
	v_sub_f32_e32 v1, v29, v2
	v_sub_f32_e32 v0, v28, v2
	v_sub_f32_e32 v5, v31, v2
	v_sub_f32_e32 v4, v30, v2
	v_pk_mul_f32 v[4:5], v[2:3], v[4:5] op_sel:[1,0]
	v_pk_mul_f32 v[0:1], v[2:3], v[0:1] op_sel:[1,0]
	v_pk_fma_f32 v[2:3], v[206:207], v[4:5], v[210:211]
	v_pk_fma_f32 v[0:1], v[204:205], v[0:1], v[208:209]
	v_cndmask_b32_e32 v3, v166, v3, vcc
	v_cndmask_b32_e32 v2, v166, v2, vcc
	v_cndmask_b32_e32 v1, v166, v1, vcc
	v_cndmask_b32_e32 v0, v166, v0, vcc
	global_store_dwordx4 v[148:149], v[0:3], off offset:576 sc1
	v_lshl_add_u64 v[4:5], v[104:105], 0, v[36:37]
	v_lshl_add_u64 v[4:5], v[4:5], 1, s[4:5]
	v_cvt_pk_bf16_f32 v0, v0, v1
	v_cvt_pk_bf16_f32 v1, v2, v3
	ds_read_b64 v[2:3], v167 offset:9472
	global_store_dwordx2 v[4:5], v[0:1], off sc1
	s_waitcnt lgkmcnt(0)
	v_sub_f32_e32 v1, v45, v2
	v_sub_f32_e32 v0, v44, v2
	v_sub_f32_e32 v5, v47, v2
	v_sub_f32_e32 v4, v46, v2
	v_pk_mul_f32 v[4:5], v[2:3], v[4:5] op_sel:[1,0]
	v_pk_mul_f32 v[0:1], v[2:3], v[0:1] op_sel:[1,0]
	v_pk_fma_f32 v[2:3], v[206:207], v[4:5], v[210:211]
	v_pk_fma_f32 v[0:1], v[204:205], v[0:1], v[208:209]
	v_cndmask_b32_e32 v3, v166, v3, vcc
	v_cndmask_b32_e32 v2, v166, v2, vcc
	v_cndmask_b32_e32 v1, v166, v1, vcc
	v_cndmask_b32_e32 v0, v166, v0, vcc
	global_store_dwordx4 v[150:151], v[0:3], off offset:576 sc1
	v_lshl_add_u64 v[4:5], v[88:89], 0, v[36:37]
	v_lshl_add_u64 v[4:5], v[4:5], 1, s[4:5]
	v_cvt_pk_bf16_f32 v0, v0, v1
	v_cvt_pk_bf16_f32 v1, v2, v3
	ds_read_b64 v[2:3], v167 offset:9600
	global_store_dwordx2 v[4:5], v[0:1], off sc1
	v_lshl_add_u64 v[4:5], v[64:65], 0, v[36:37]
	s_waitcnt lgkmcnt(0)
	v_sub_f32_e32 v1, v17, v2
	v_sub_f32_e32 v0, v16, v2
	v_sub_f32_e32 v7, v19, v2
	v_sub_f32_e32 v6, v18, v2
	v_pk_mul_f32 v[6:7], v[2:3], v[6:7] op_sel:[1,0]
	v_pk_mul_f32 v[0:1], v[2:3], v[0:1] op_sel:[1,0]
	v_pk_fma_f32 v[2:3], v[206:207], v[6:7], v[210:211]
	v_pk_fma_f32 v[0:1], v[204:205], v[0:1], v[208:209]
	v_cndmask_b32_e32 v3, v166, v3, vcc
	v_cndmask_b32_e32 v2, v166, v2, vcc
	v_cndmask_b32_e32 v1, v166, v1, vcc
	v_cndmask_b32_e32 v0, v166, v0, vcc
	global_store_dwordx4 v[152:153], v[0:3], off offset:576 sc1
	s_nop 1
	v_cvt_pk_bf16_f32 v0, v0, v1
	v_cvt_pk_bf16_f32 v1, v2, v3
	v_lshl_add_u64 v[2:3], v[4:5], 1, s[4:5]
	global_store_dwordx2 v[2:3], v[0:1], off sc1

.LBB0_1858:
	s_or_b64 exec, exec, s[2:3]
	v_lshl_add_u64 v[140:141], s[8:9], 0, v[136:137]
	v_add_co_u32_e32 v128, vcc, 0x1000, v140
	v_lshl_add_u64 v[142:143], s[10:11], 0, v[136:137]
	s_nop 0
	v_addc_co_u32_e32 v129, vcc, 0, v141, vcc
	v_add_co_u32_e32 v132, vcc, 0x1000, v142
	s_waitcnt lgkmcnt(0)
	s_barrier
	s_nop 0
	v_addc_co_u32_e32 v133, vcc, 0, v143, vcc
	global_load_dwordx4 v[128:131], v[128:129], off
	v_or_b32_e32 v144, s20, v138
	global_load_dwordx4 v[132:135], v[132:133], off
	s_mov_b64 s[0:1], 0x1000
	v_lshl_add_u64 v[138:139], v[140:141], 0, s[0:1]
	v_lshl_add_u64 v[140:141], v[142:143], 0, s[0:1]
	v_lshl_add_u32 v142, v144, 3, 0
	v_add_u32_e32 v149, 0x2000, v142
	ds_read2_b64 v[152:155], v149 offset1:16
	ds_read2_b64 v[156:159], v149 offset0:32 offset1:48
	v_add_u32_e32 v160, s22, v144
	v_add_u32_e32 v142, 16, v160
	v_add_u32_e32 v144, 32, v160
	v_ashrrev_i32_e32 v143, 31, v142
	v_ashrrev_i32_e32 v145, 31, v144
	v_ashrrev_i32_e32 v161, 31, v160
	v_lshlrev_b64 v[142:143], 12, v[142:143]
	v_lshlrev_b64 v[144:145], 12, v[144:145]
	s_waitcnt lgkmcnt(1)
	v_sub_f32_e32 v115, v115, v152
	v_sub_f32_e32 v114, v114, v152
	v_sub_f32_e32 v113, v113, v152
	v_sub_f32_e32 v112, v112, v152
	v_lshlrev_b64 v[146:147], 12, v[160:161]
	v_lshl_add_u64 v[142:143], s[12:13], 0, v[142:143]
	v_lshl_add_u64 v[164:165], s[12:13], 0, v[144:145]
	v_sub_f32_e32 v123, v123, v154
	v_sub_f32_e32 v122, v122, v154
	v_sub_f32_e32 v121, v121, v154
	v_sub_f32_e32 v120, v120, v154
	s_waitcnt lgkmcnt(0)
	v_sub_f32_e32 v127, v127, v156
	v_sub_f32_e32 v126, v126, v156
	v_sub_f32_e32 v125, v125, v156
	v_sub_f32_e32 v124, v124, v156
	v_pk_mul_f32 v[112:113], v[152:153], v[112:113] op_sel:[1,0]
	v_pk_mul_f32 v[114:115], v[152:153], v[114:115] op_sel:[1,0]
	v_mov_b32_e32 v148, 0x7fc00000
	v_lshl_add_u64 v[146:147], s[12:13], 0, v[146:147]
	v_lshl_add_u64 v[144:145], v[142:143], 0, v[136:137]
	v_lshl_add_u64 v[142:143], v[164:165], 0, v[136:137]
	v_sub_f32_e32 v165, v119, v158
	v_sub_f32_e32 v164, v118, v158
	v_pk_mul_f32 v[118:119], v[154:155], v[120:121] op_sel:[1,0]
	v_pk_mul_f32 v[120:121], v[154:155], v[122:123] op_sel:[1,0]
	v_pk_mul_f32 v[122:123], v[156:157], v[124:125] op_sel:[1,0]
	v_pk_mul_f32 v[124:125], v[156:157], v[126:127] op_sel:[1,0]
	v_cmp_eq_u32_e32 vcc, 0, v150
	v_lshl_add_u64 v[146:147], v[146:147], 0, v[136:137]
	v_sub_f32_e32 v117, v117, v158
	v_sub_f32_e32 v116, v116, v158
	v_add_u32_e32 v162, 48, v160
	v_ashrrev_i32_e32 v163, 31, v162
	global_load_dwordx4 v[188:191], v[138:139], off offset:64
	global_load_dwordx4 v[192:195], v[140:141], off offset:64
	global_load_dwordx4 v[196:199], v[138:139], off offset:512
	global_load_dwordx4 v[200:203], v[140:141], off offset:512
	global_load_dwordx4 v[204:207], v[138:139], off offset:576
	global_load_dwordx4 v[208:211], v[140:141], off offset:576
	s_waitcnt vmcnt(0)
	v_pk_fma_f32 v[114:115], v[130:131], v[114:115], v[134:135]
	v_pk_fma_f32 v[112:113], v[128:129], v[112:113], v[132:133]
	v_pk_fma_f32 v[120:121], v[130:131], v[120:121], v[134:135]
	v_pk_fma_f32 v[118:119], v[128:129], v[118:119], v[132:133]
	v_pk_fma_f32 v[124:125], v[130:131], v[124:125], v[134:135]
	v_pk_fma_f32 v[122:123], v[128:129], v[122:123], v[132:133]
	v_cndmask_b32_e32 v115, v148, v115, vcc
	v_cndmask_b32_e32 v114, v148, v114, vcc
	v_cndmask_b32_e32 v113, v148, v113, vcc
	v_cndmask_b32_e32 v112, v148, v112, vcc
	v_cndmask_b32_e32 v121, v148, v121, vcc
	v_cndmask_b32_e32 v120, v148, v120, vcc
	v_cndmask_b32_e32 v119, v148, v119, vcc
	v_cndmask_b32_e32 v118, v148, v118, vcc
	v_cndmask_b32_e32 v125, v148, v125, vcc
	v_cndmask_b32_e32 v124, v148, v124, vcc
	v_cndmask_b32_e32 v123, v148, v123, vcc
	v_cndmask_b32_e32 v122, v148, v122, vcc
	global_store_dwordx4 v[146:147], v[112:115], off sc1
	global_store_dwordx4 v[144:145], v[118:121], off sc1
	global_store_dwordx4 v[142:143], v[122:125], off sc1
	ds_read2_b64 v[118:121], v149 offset0:128 offset1:144
	v_pk_mul_f32 v[112:113], v[158:159], v[116:117] op_sel:[1,0]
	v_pk_mul_f32 v[114:115], v[158:159], v[164:165] op_sel:[1,0]
	v_pk_fma_f32 v[112:113], v[128:129], v[112:113], v[132:133]
	v_pk_fma_f32 v[114:115], v[130:131], v[114:115], v[134:135]
	s_waitcnt lgkmcnt(0)
	v_sub_f32_e32 v99, v99, v118
	v_cndmask_b32_e32 v117, v148, v115, vcc
	v_cndmask_b32_e32 v116, v148, v114, vcc
	v_cndmask_b32_e32 v115, v148, v113, vcc
	v_cndmask_b32_e32 v114, v148, v112, vcc
	v_lshlrev_b64 v[112:113], 12, v[162:163]
	v_sub_f32_e32 v98, v98, v118
	v_sub_f32_e32 v97, v97, v118
	v_sub_f32_e32 v96, v96, v118
	v_sub_f32_e32 v83, v83, v120
	v_sub_f32_e32 v82, v82, v120
	v_sub_f32_e32 v81, v81, v120
	v_sub_f32_e32 v80, v80, v120
	v_lshl_add_u64 v[112:113], s[12:13], 0, v[112:113]
	v_add_u32_e32 v122, 0x80, v160
	v_pk_mul_f32 v[96:97], v[118:119], v[96:97] op_sel:[1,0]
	v_pk_mul_f32 v[98:99], v[118:119], v[98:99] op_sel:[1,0]
	v_pk_mul_f32 v[80:81], v[120:121], v[80:81] op_sel:[1,0]
	v_pk_mul_f32 v[82:83], v[120:121], v[82:83] op_sel:[1,0]
	ds_read2_b64 v[118:121], v149 offset0:160 offset1:176
	v_lshl_add_u64 v[112:113], v[112:113], 0, v[136:137]
	v_ashrrev_i32_e32 v123, 31, v122
	v_pk_fma_f32 v[96:97], v[128:129], v[96:97], v[132:133]
	global_store_dwordx4 v[112:113], v[114:117], off sc1
	v_pk_fma_f32 v[98:99], v[130:131], v[98:99], v[134:135]
	v_pk_fma_f32 v[80:81], v[128:129], v[80:81], v[132:133]
	v_cndmask_b32_e32 v115, v148, v97, vcc
	v_cndmask_b32_e32 v114, v148, v96, vcc
	v_lshlrev_b64 v[96:97], 12, v[122:123]
	v_cndmask_b32_e32 v116, v148, v98, vcc
	v_lshl_add_u64 v[96:97], s[12:13], 0, v[96:97]
	v_add_u32_e32 v98, 0x90, v160
	v_cndmask_b32_e32 v117, v148, v99, vcc
	v_lshl_add_u64 v[96:97], v[96:97], 0, v[136:137]
	v_ashrrev_i32_e32 v99, 31, v98
	global_store_dwordx4 v[96:97], v[114:117], off sc1
	v_pk_fma_f32 v[82:83], v[130:131], v[82:83], v[134:135]
	s_waitcnt lgkmcnt(0)
	v_sub_f32_e32 v45, v45, v118
	v_cndmask_b32_e32 v115, v148, v81, vcc
	v_cndmask_b32_e32 v114, v148, v80, vcc
	v_lshlrev_b64 v[80:81], 12, v[98:99]
	v_sub_f32_e32 v44, v44, v118
	v_cndmask_b32_e32 v116, v148, v82, vcc
	v_lshl_add_u64 v[80:81], s[12:13], 0, v[80:81]
	v_add_u32_e32 v82, 0xa0, v160
	v_sub_f32_e32 v47, v47, v118
	v_sub_f32_e32 v46, v46, v118
	v_pk_mul_f32 v[44:45], v[118:119], v[44:45] op_sel:[1,0]
	v_cndmask_b32_e32 v117, v148, v83, vcc
	v_lshl_add_u64 v[80:81], v[80:81], 0, v[136:137]
	v_ashrrev_i32_e32 v83, 31, v82
	v_pk_mul_f32 v[46:47], v[118:119], v[46:47] op_sel:[1,0]
	v_pk_fma_f32 v[44:45], v[128:129], v[44:45], v[132:133]
	global_store_dwordx4 v[80:81], v[114:117], off sc1
	v_pk_fma_f32 v[46:47], v[130:131], v[46:47], v[134:135]
	v_sub_f32_e32 v17, v17, v120
	v_cndmask_b32_e32 v115, v148, v45, vcc
	v_cndmask_b32_e32 v114, v148, v44, vcc
	v_lshlrev_b64 v[44:45], 12, v[82:83]
	v_sub_f32_e32 v16, v16, v120
	v_cndmask_b32_e32 v116, v148, v46, vcc
	v_lshl_add_u64 v[44:45], s[12:13], 0, v[44:45]
	v_add_u32_e32 v46, 0xb0, v160
	v_pk_mul_f32 v[16:17], v[120:121], v[16:17] op_sel:[1,0]
	v_cndmask_b32_e32 v117, v148, v47, vcc
	v_lshl_add_u64 v[44:45], v[44:45], 0, v[136:137]
	v_ashrrev_i32_e32 v47, 31, v46
	v_sub_f32_e32 v19, v19, v120
	v_sub_f32_e32 v18, v18, v120
	v_pk_fma_f32 v[16:17], v[128:129], v[16:17], v[132:133]
	global_store_dwordx4 v[44:45], v[114:117], off sc1
	v_pk_mul_f32 v[18:19], v[120:121], v[18:19] op_sel:[1,0]
	s_nop 0
	v_cndmask_b32_e32 v115, v148, v17, vcc
	v_cndmask_b32_e32 v114, v148, v16, vcc
	v_lshlrev_b64 v[16:17], 12, v[46:47]
	v_pk_fma_f32 v[18:19], v[130:131], v[18:19], v[134:135]
	v_lshl_add_u64 v[16:17], s[12:13], 0, v[16:17]
	v_cndmask_b32_e32 v117, v148, v19, vcc
	v_cndmask_b32_e32 v116, v148, v18, vcc
	v_lshl_add_u64 v[16:17], v[16:17], 0, v[136:137]
	global_store_dwordx4 v[16:17], v[114:117], off sc1
	ds_read2_b64 v[122:125], v149 offset1:16
	s_waitcnt lgkmcnt(0)
	v_sub_f32_e32 v19, v89, v122
	v_sub_f32_e32 v18, v88, v122
	v_pk_mul_f32 v[18:19], v[122:123], v[18:19] op_sel:[1,0]
	v_sub_f32_e32 v47, v91, v122
	v_sub_f32_e32 v46, v90, v122
	v_pk_mul_f32 v[46:47], v[122:123], v[46:47] op_sel:[1,0]
	v_pk_fma_f32 v[18:19], v[188:189], v[18:19], v[192:193]
	s_nop 0
	v_cndmask_b32_e32 v89, v148, v19, vcc
	v_cndmask_b32_e32 v88, v148, v18, vcc
	v_sub_f32_e32 v19, v101, v124
	v_sub_f32_e32 v18, v100, v124
	ds_read2_b64 v[98:101], v149 offset0:32 offset1:48
	v_pk_fma_f32 v[46:47], v[190:191], v[46:47], v[194:195]
	v_pk_mul_f32 v[18:19], v[124:125], v[18:19] op_sel:[1,0]
	v_cndmask_b32_e32 v91, v148, v47, vcc
	v_cndmask_b32_e32 v90, v148, v46, vcc
	v_sub_f32_e32 v47, v103, v124
	v_sub_f32_e32 v46, v102, v124
	v_pk_mul_f32 v[46:47], v[124:125], v[46:47] op_sel:[1,0]
	v_pk_fma_f32 v[18:19], v[188:189], v[18:19], v[192:193]
	v_pk_fma_f32 v[46:47], v[190:191], v[46:47], v[194:195]
	global_store_dwordx4 v[146:147], v[88:91], off offset:64 sc1
	s_nop 1
	v_cndmask_b32_e32 v91, v148, v47, vcc
	v_cndmask_b32_e32 v90, v148, v46, vcc
	v_cndmask_b32_e32 v89, v148, v19, vcc
	v_cndmask_b32_e32 v88, v148, v18, vcc
	s_waitcnt lgkmcnt(0)
	v_sub_f32_e32 v19, v105, v98
	v_sub_f32_e32 v18, v104, v98
	v_sub_f32_e32 v47, v107, v98
	v_sub_f32_e32 v46, v106, v98
	v_pk_mul_f32 v[46:47], v[98:99], v[46:47] op_sel:[1,0]
	v_pk_mul_f32 v[18:19], v[98:99], v[18:19] op_sel:[1,0]
	v_pk_fma_f32 v[46:47], v[190:191], v[46:47], v[194:195]
	v_pk_fma_f32 v[18:19], v[188:189], v[18:19], v[192:193]
	global_store_dwordx4 v[144:145], v[88:91], off offset:64 sc1
	s_nop 1
	v_cndmask_b32_e32 v91, v148, v47, vcc
	v_cndmask_b32_e32 v90, v148, v46, vcc
	v_cndmask_b32_e32 v89, v148, v19, vcc
	v_cndmask_b32_e32 v88, v148, v18, vcc
	v_sub_f32_e32 v19, v109, v100
	v_sub_f32_e32 v18, v108, v100
	v_sub_f32_e32 v47, v111, v100
	v_sub_f32_e32 v46, v110, v100
	v_pk_mul_f32 v[46:47], v[100:101], v[46:47] op_sel:[1,0]
	v_pk_mul_f32 v[18:19], v[100:101], v[18:19] op_sel:[1,0]
	ds_read2_b64 v[98:101], v149 offset0:128 offset1:144
	v_pk_fma_f32 v[18:19], v[188:189], v[18:19], v[192:193]
	v_pk_fma_f32 v[46:47], v[190:191], v[46:47], v[194:195]
	global_store_dwordx4 v[142:143], v[88:91], off offset:64 sc1
	s_nop 1
	v_cndmask_b32_e32 v91, v148, v47, vcc
	v_cndmask_b32_e32 v90, v148, v46, vcc
	v_cndmask_b32_e32 v89, v148, v19, vcc
	v_cndmask_b32_e32 v88, v148, v18, vcc
	s_waitcnt lgkmcnt(0)
	v_sub_f32_e32 v19, v93, v98
	v_sub_f32_e32 v18, v92, v98
	v_sub_f32_e32 v47, v95, v98
	v_sub_f32_e32 v46, v94, v98
	v_pk_mul_f32 v[46:47], v[98:99], v[46:47] op_sel:[1,0]
	v_pk_mul_f32 v[18:19], v[98:99], v[18:19] op_sel:[1,0]
	v_pk_fma_f32 v[46:47], v[190:191], v[46:47], v[194:195]
	v_pk_fma_f32 v[18:19], v[188:189], v[18:19], v[192:193]
	global_store_dwordx4 v[112:113], v[88:91], off offset:64 sc1
	s_nop 1
	v_cndmask_b32_e32 v91, v148, v47, vcc
	v_cndmask_b32_e32 v90, v148, v46, vcc
	v_cndmask_b32_e32 v89, v148, v19, vcc
	v_cndmask_b32_e32 v88, v148, v18, vcc
	global_store_dwordx4 v[96:97], v[88:91], off offset:64 sc1
	ds_read2_b64 v[88:91], v149 offset0:160 offset1:176
	v_sub_f32_e32 v19, v73, v100
	v_sub_f32_e32 v18, v72, v100
	v_pk_mul_f32 v[18:19], v[100:101], v[18:19] op_sel:[1,0]
	v_sub_f32_e32 v47, v75, v100
	v_pk_fma_f32 v[18:19], v[188:189], v[18:19], v[192:193]
	v_sub_f32_e32 v46, v74, v100
	v_cndmask_b32_e32 v73, v148, v19, vcc
	v_cndmask_b32_e32 v72, v148, v18, vcc
	s_waitcnt lgkmcnt(0)
	v_sub_f32_e32 v19, v41, v88
	v_sub_f32_e32 v18, v40, v88
	v_sub_f32_e32 v41, v43, v88
	v_sub_f32_e32 v40, v42, v88
	v_sub_f32_e32 v13, v13, v90
	v_sub_f32_e32 v12, v12, v90
	v_sub_f32_e32 v15, v15, v90
	v_sub_f32_e32 v14, v14, v90
	v_pk_mul_f32 v[46:47], v[100:101], v[46:47] op_sel:[1,0]
	v_pk_mul_f32 v[40:41], v[88:89], v[40:41] op_sel:[1,0]
	v_pk_mul_f32 v[18:19], v[88:89], v[18:19] op_sel:[1,0]
	v_pk_mul_f32 v[14:15], v[90:91], v[14:15] op_sel:[1,0]
	v_pk_mul_f32 v[12:13], v[90:91], v[12:13] op_sel:[1,0]
	v_pk_fma_f32 v[46:47], v[190:191], v[46:47], v[194:195]
	v_pk_fma_f32 v[18:19], v[188:189], v[18:19], v[192:193]
	v_pk_fma_f32 v[40:41], v[190:191], v[40:41], v[194:195]
	v_pk_fma_f32 v[12:13], v[188:189], v[12:13], v[192:193]
	v_pk_fma_f32 v[14:15], v[190:191], v[14:15], v[194:195]
	v_cndmask_b32_e32 v75, v148, v47, vcc
	v_cndmask_b32_e32 v74, v148, v46, vcc
	v_cndmask_b32_e32 v43, v148, v41, vcc
	v_cndmask_b32_e32 v42, v148, v40, vcc
	v_cndmask_b32_e32 v41, v148, v19, vcc
	v_cndmask_b32_e32 v40, v148, v18, vcc
	v_cndmask_b32_e32 v15, v148, v15, vcc
	v_cndmask_b32_e32 v14, v148, v14, vcc
	v_cndmask_b32_e32 v13, v148, v13, vcc
	v_cndmask_b32_e32 v12, v148, v12, vcc
	global_store_dwordx4 v[80:81], v[72:75], off offset:64 sc1
	global_store_dwordx4 v[44:45], v[40:43], off offset:64 sc1
	global_store_dwordx4 v[16:17], v[12:15], off offset:64 sc1
	ds_read2_b64 v[72:75], v149 offset1:16
	s_waitcnt lgkmcnt(0)
	v_sub_f32_e32 v19, v53, v72
	v_sub_f32_e32 v18, v52, v72
	v_sub_f32_e32 v47, v55, v72
	v_sub_f32_e32 v46, v54, v72
	v_pk_mul_f32 v[46:47], v[72:73], v[46:47] op_sel:[1,0]
	v_pk_mul_f32 v[18:19], v[72:73], v[18:19] op_sel:[1,0]
	v_pk_fma_f32 v[46:47], v[198:199], v[46:47], v[202:203]
	v_pk_fma_f32 v[18:19], v[196:197], v[18:19], v[200:201]
	v_cndmask_b32_e32 v55, v148, v47, vcc
	v_cndmask_b32_e32 v54, v148, v46, vcc
	v_cndmask_b32_e32 v53, v148, v19, vcc
	v_cndmask_b32_e32 v52, v148, v18, vcc
	v_sub_f32_e32 v19, v61, v74
	v_sub_f32_e32 v18, v60, v74
	v_sub_f32_e32 v47, v63, v74
	v_sub_f32_e32 v46, v62, v74
	ds_read2_b64 v[60:63], v149 offset0:32 offset1:48
	v_pk_mul_f32 v[46:47], v[74:75], v[46:47] op_sel:[1,0]
	v_pk_mul_f32 v[18:19], v[74:75], v[18:19] op_sel:[1,0]
	v_pk_fma_f32 v[46:47], v[198:199], v[46:47], v[202:203]
	v_pk_fma_f32 v[18:19], v[196:197], v[18:19], v[200:201]
	global_store_dwordx4 v[146:147], v[52:55], off offset:512 sc1
	s_nop 1
	v_cndmask_b32_e32 v55, v148, v47, vcc
	v_cndmask_b32_e32 v54, v148, v46, vcc
	v_cndmask_b32_e32 v53, v148, v19, vcc
	v_cndmask_b32_e32 v52, v148, v18, vcc
	s_waitcnt lgkmcnt(0)
	v_sub_f32_e32 v19, v69, v60
	v_sub_f32_e32 v18, v68, v60
	v_sub_f32_e32 v47, v71, v60
	v_sub_f32_e32 v46, v70, v60
	v_pk_mul_f32 v[46:47], v[60:61], v[46:47] op_sel:[1,0]
	v_pk_mul_f32 v[18:19], v[60:61], v[18:19] op_sel:[1,0]
	v_pk_fma_f32 v[46:47], v[198:199], v[46:47], v[202:203]
	v_pk_fma_f32 v[18:19], v[196:197], v[18:19], v[200:201]
	global_store_dwordx4 v[144:145], v[52:55], off offset:512 sc1
	s_nop 1
	v_cndmask_b32_e32 v55, v148, v47, vcc
	v_cndmask_b32_e32 v54, v148, v46, vcc
	v_cndmask_b32_e32 v53, v148, v19, vcc
	v_cndmask_b32_e32 v52, v148, v18, vcc
	v_sub_f32_e32 v19, v77, v62
	v_sub_f32_e32 v18, v76, v62
	v_sub_f32_e32 v47, v79, v62
	v_sub_f32_e32 v46, v78, v62
	v_pk_mul_f32 v[46:47], v[62:63], v[46:47] op_sel:[1,0]
	v_pk_mul_f32 v[18:19], v[62:63], v[18:19] op_sel:[1,0]
	ds_read2_b64 v[60:63], v149 offset0:128 offset1:144
	v_pk_fma_f32 v[18:19], v[196:197], v[18:19], v[200:201]
	v_pk_fma_f32 v[46:47], v[198:199], v[46:47], v[202:203]
	global_store_dwordx4 v[142:143], v[52:55], off offset:512 sc1
	s_nop 1
	v_cndmask_b32_e32 v55, v148, v47, vcc
	v_cndmask_b32_e32 v54, v148, v46, vcc
	v_cndmask_b32_e32 v53, v148, v19, vcc
	v_cndmask_b32_e32 v52, v148, v18, vcc
	s_waitcnt lgkmcnt(0)
	v_sub_f32_e32 v19, v85, v60
	v_sub_f32_e32 v18, v84, v60
	v_sub_f32_e32 v47, v87, v60
	v_sub_f32_e32 v46, v86, v60
	v_pk_mul_f32 v[46:47], v[60:61], v[46:47] op_sel:[1,0]
	v_pk_mul_f32 v[18:19], v[60:61], v[18:19] op_sel:[1,0]
	v_pk_fma_f32 v[46:47], v[198:199], v[46:47], v[202:203]
	v_pk_fma_f32 v[18:19], v[196:197], v[18:19], v[200:201]
	global_store_dwordx4 v[112:113], v[52:55], off offset:512 sc1
	s_nop 1
	v_cndmask_b32_e32 v55, v148, v47, vcc
	v_cndmask_b32_e32 v54, v148, v46, vcc
	v_cndmask_b32_e32 v53, v148, v19, vcc
	v_cndmask_b32_e32 v52, v148, v18, vcc
	v_sub_f32_e32 v19, v65, v62
	v_sub_f32_e32 v18, v64, v62
	v_sub_f32_e32 v47, v67, v62
	v_sub_f32_e32 v46, v66, v62
	v_pk_mul_f32 v[46:47], v[62:63], v[46:47] op_sel:[1,0]
	v_pk_mul_f32 v[18:19], v[62:63], v[18:19] op_sel:[1,0]
	ds_read2_b64 v[60:63], v149 offset0:160 offset1:176
	v_pk_fma_f32 v[18:19], v[196:197], v[18:19], v[200:201]
	global_store_dwordx4 v[96:97], v[52:55], off offset:512 sc1
	v_pk_fma_f32 v[46:47], v[198:199], v[46:47], v[202:203]
	s_waitcnt lgkmcnt(0)
	v_sub_f32_e32 v5, v5, v62
	v_cndmask_b32_e32 v53, v148, v19, vcc
	v_cndmask_b32_e32 v52, v148, v18, vcc
	v_sub_f32_e32 v19, v33, v60
	v_sub_f32_e32 v18, v32, v60
	v_sub_f32_e32 v33, v35, v60
	v_sub_f32_e32 v32, v34, v60
	v_sub_f32_e32 v4, v4, v62
	v_sub_f32_e32 v7, v7, v62
	v_sub_f32_e32 v6, v6, v62
	v_pk_mul_f32 v[32:33], v[60:61], v[32:33] op_sel:[1,0]
	v_pk_mul_f32 v[18:19], v[60:61], v[18:19] op_sel:[1,0]
	v_pk_mul_f32 v[6:7], v[62:63], v[6:7] op_sel:[1,0]
	v_pk_mul_f32 v[4:5], v[62:63], v[4:5] op_sel:[1,0]
	v_pk_fma_f32 v[18:19], v[196:197], v[18:19], v[200:201]
	v_pk_fma_f32 v[32:33], v[198:199], v[32:33], v[202:203]
	v_pk_fma_f32 v[4:5], v[196:197], v[4:5], v[200:201]
	v_pk_fma_f32 v[6:7], v[198:199], v[6:7], v[202:203]
	v_cndmask_b32_e32 v55, v148, v47, vcc
	v_cndmask_b32_e32 v54, v148, v46, vcc
	v_cndmask_b32_e32 v35, v148, v33, vcc
	v_cndmask_b32_e32 v34, v148, v32, vcc
	v_cndmask_b32_e32 v33, v148, v19, vcc
	v_cndmask_b32_e32 v32, v148, v18, vcc
	v_cndmask_b32_e32 v7, v148, v7, vcc
	v_cndmask_b32_e32 v6, v148, v6, vcc
	v_cndmask_b32_e32 v5, v148, v5, vcc
	v_cndmask_b32_e32 v4, v148, v4, vcc
	global_store_dwordx4 v[80:81], v[52:55], off offset:512 sc1
	global_store_dwordx4 v[44:45], v[32:35], off offset:512 sc1
	global_store_dwordx4 v[16:17], v[4:7], off offset:512 sc1
	ds_read2_b64 v[32:35], v149 offset1:16
	s_waitcnt lgkmcnt(0)
	v_sub_f32_e32 v9, v9, v32
	v_sub_f32_e32 v8, v8, v32
	v_sub_f32_e32 v11, v11, v32
	v_sub_f32_e32 v10, v10, v32
	v_pk_mul_f32 v[10:11], v[32:33], v[10:11] op_sel:[1,0]
	v_pk_mul_f32 v[8:9], v[32:33], v[8:9] op_sel:[1,0]
	v_pk_fma_f32 v[10:11], v[206:207], v[10:11], v[210:211]
	v_pk_fma_f32 v[8:9], v[204:205], v[8:9], v[208:209]
	v_cndmask_b32_e32 v11, v148, v11, vcc
	v_cndmask_b32_e32 v10, v148, v10, vcc
	v_cndmask_b32_e32 v9, v148, v9, vcc
	v_cndmask_b32_e32 v8, v148, v8, vcc
	global_store_dwordx4 v[146:147], v[8:11], off offset:576 sc1
	s_nop 1
	v_sub_f32_e32 v9, v21, v34
	v_sub_f32_e32 v8, v20, v34
	ds_read2_b64 v[18:21], v149 offset0:32 offset1:48
	v_sub_f32_e32 v11, v23, v34
	v_sub_f32_e32 v10, v22, v34
	v_pk_mul_f32 v[10:11], v[34:35], v[10:11] op_sel:[1,0]
	v_pk_mul_f32 v[8:9], v[34:35], v[8:9] op_sel:[1,0]
	v_pk_fma_f32 v[10:11], v[206:207], v[10:11], v[210:211]
	v_pk_fma_f32 v[8:9], v[204:205], v[8:9], v[208:209]
	v_cndmask_b32_e32 v11, v148, v11, vcc
	v_cndmask_b32_e32 v10, v148, v10, vcc
	v_cndmask_b32_e32 v9, v148, v9, vcc
	v_cndmask_b32_e32 v8, v148, v8, vcc
	global_store_dwordx4 v[144:145], v[8:11], off offset:576 sc1
	s_waitcnt lgkmcnt(0)
	s_nop 0
	v_sub_f32_e32 v9, v29, v18
	v_sub_f32_e32 v8, v28, v18
	v_sub_f32_e32 v11, v31, v18
	v_sub_f32_e32 v10, v30, v18
	v_pk_mul_f32 v[10:11], v[18:19], v[10:11] op_sel:[1,0]
	v_pk_mul_f32 v[8:9], v[18:19], v[8:9] op_sel:[1,0]
	v_pk_fma_f32 v[10:11], v[206:207], v[10:11], v[210:211]
	v_pk_fma_f32 v[8:9], v[204:205], v[8:9], v[208:209]
	v_cndmask_b32_e32 v11, v148, v11, vcc
	v_cndmask_b32_e32 v10, v148, v10, vcc
	v_cndmask_b32_e32 v9, v148, v9, vcc
	v_cndmask_b32_e32 v8, v148, v8, vcc
	global_store_dwordx4 v[142:143], v[8:11], off offset:576 sc1
	s_nop 1
	v_sub_f32_e32 v9, v37, v20
	v_sub_f32_e32 v8, v36, v20
	v_sub_f32_e32 v11, v39, v20
	v_sub_f32_e32 v10, v38, v20
	v_pk_mul_f32 v[10:11], v[20:21], v[10:11] op_sel:[1,0]
	v_pk_mul_f32 v[8:9], v[20:21], v[8:9] op_sel:[1,0]
	ds_read2_b64 v[18:21], v149 offset0:128 offset1:144
	v_pk_fma_f32 v[8:9], v[204:205], v[8:9], v[208:209]
	v_pk_fma_f32 v[10:11], v[206:207], v[10:11], v[210:211]
	v_cndmask_b32_e32 v9, v148, v9, vcc
	v_cndmask_b32_e32 v11, v148, v11, vcc
	v_cndmask_b32_e32 v10, v148, v10, vcc
	v_cndmask_b32_e32 v8, v148, v8, vcc
	global_store_dwordx4 v[112:113], v[8:11], off offset:576 sc1
	s_waitcnt lgkmcnt(0)
	s_nop 0
	v_sub_f32_e32 v9, v49, v18
	v_sub_f32_e32 v8, v48, v18
	v_sub_f32_e32 v11, v51, v18
	v_sub_f32_e32 v10, v50, v18
	v_pk_mul_f32 v[10:11], v[18:19], v[10:11] op_sel:[1,0]
	v_pk_mul_f32 v[8:9], v[18:19], v[8:9] op_sel:[1,0]
	v_pk_fma_f32 v[10:11], v[206:207], v[10:11], v[210:211]
	v_pk_fma_f32 v[8:9], v[204:205], v[8:9], v[208:209]
	v_cndmask_b32_e32 v11, v148, v11, vcc
	v_cndmask_b32_e32 v10, v148, v10, vcc
	v_cndmask_b32_e32 v9, v148, v9, vcc
	v_cndmask_b32_e32 v8, v148, v8, vcc
	global_store_dwordx4 v[96:97], v[8:11], off offset:576 sc1
	s_nop 1
	v_sub_f32_e32 v9, v57, v20
	v_sub_f32_e32 v8, v56, v20
	v_sub_f32_e32 v11, v59, v20
	v_sub_f32_e32 v10, v58, v20
	v_pk_mul_f32 v[10:11], v[20:21], v[10:11] op_sel:[1,0]
	v_pk_mul_f32 v[8:9], v[20:21], v[8:9] op_sel:[1,0]
	ds_read2_b64 v[18:21], v149 offset0:160 offset1:176
	v_pk_fma_f32 v[8:9], v[204:205], v[8:9], v[208:209]
	v_pk_fma_f32 v[10:11], v[206:207], v[10:11], v[210:211]
	v_cndmask_b32_e32 v9, v148, v9, vcc
	v_cndmask_b32_e32 v11, v148, v11, vcc
	v_cndmask_b32_e32 v10, v148, v10, vcc
	v_cndmask_b32_e32 v8, v148, v8, vcc
	global_store_dwordx4 v[80:81], v[8:11], off offset:576 sc1
	s_waitcnt lgkmcnt(0)
	v_sub_f32_e32 v1, v1, v20
	v_sub_f32_e32 v0, v0, v20
	v_sub_f32_e32 v9, v25, v18
	v_sub_f32_e32 v8, v24, v18
	v_sub_f32_e32 v11, v27, v18
	v_sub_f32_e32 v10, v26, v18
	v_sub_f32_e32 v3, v3, v20
	v_sub_f32_e32 v2, v2, v20
	v_pk_mul_f32 v[10:11], v[18:19], v[10:11] op_sel:[1,0]
	v_pk_mul_f32 v[8:9], v[18:19], v[8:9] op_sel:[1,0]
	v_pk_mul_f32 v[2:3], v[20:21], v[2:3] op_sel:[1,0]
	v_pk_mul_f32 v[0:1], v[20:21], v[0:1] op_sel:[1,0]
	v_pk_fma_f32 v[8:9], v[204:205], v[8:9], v[208:209]
	v_pk_fma_f32 v[10:11], v[206:207], v[10:11], v[210:211]
	v_pk_fma_f32 v[0:1], v[204:205], v[0:1], v[208:209]
	v_pk_fma_f32 v[2:3], v[206:207], v[2:3], v[210:211]
	v_cndmask_b32_e32 v11, v148, v11, vcc
	v_cndmask_b32_e32 v10, v148, v10, vcc
	v_cndmask_b32_e32 v9, v148, v9, vcc
	v_cndmask_b32_e32 v8, v148, v8, vcc
	v_cndmask_b32_e32 v3, v148, v3, vcc
	v_cndmask_b32_e32 v2, v148, v2, vcc
	v_cndmask_b32_e32 v1, v148, v1, vcc
	v_cndmask_b32_e32 v0, v148, v0, vcc
	global_store_dwordx4 v[44:45], v[8:11], off offset:576 sc1
	global_store_dwordx4 v[16:17], v[0:3], off offset:576 sc1
